# GEMM K-loops: back edge rotated (counter/pointer updates, exit test and next iteration's scalar address selects moved in front of the loop-back barrier; exit path has its own barrier copy)
# baseline (speedup 1.0000x reference)
; #define PG8_STAGE(bufoff, gbase, voff) do { _Pragma("unroll") for (int _i = 0; _i < 2; ++_i) \
;         __builtin_amdgcn_global_load_lds((const unsigned*)((const char*)(gbase) + (voff)[_i]), (PG8_LAS unsigned*)(lds + (bufoff) + ldsw + _i * 8192), 16, 0, 0); } while (0)
; #define PG8_LDA(dst, b, h) do { _Pragma("unroll") for (int m = 0; m < 4; ++m) _Pragma("unroll") for (int k = 0; k < 2; ++k) dst[m][k] = *(const PG8_LAS bf16x8*)(lds + PG8_SA(b, h) + aoff + m * 2048 + k * 1024); } while (0)
; #define PG8_LDB(dst, b, h) do { _Pragma("unroll") for (int n = 0; n < 2; ++n) _Pragma("unroll") for (int k = 0; k < 2; ++k) dst[n][k] = *(const PG8_LAS bf16x8*)(lds + PG8_SB(b, h) + boff + n * 2048 + k * 1024); } while (0)
; #define PG8_MMA(ai, bj, At, Bt) do { __builtin_amdgcn_s_setprio(1); _Pragma("unroll") for (int m = 0; m < 4; ++m) _Pragma("unroll") for (int n = 0; n < 2; ++n) _Pragma("unroll") for (int k = 0; k < 2; ++k) \
;         acc[ai][bj][m][n] = __builtin_amdgcn_mfma_f32_16x16x32_bf16(Bt[n][k], At[m][k], acc[ai][bj][m][n], 0, 0, 0); __builtin_amdgcn_s_setprio(0); } while (0)
; #define PG8_WAIT_V(n) asm volatile("s_waitcnt vmcnt(" #n ")" ::: "memory")
; #define PG8_WAIT_L(n) asm volatile("s_waitcnt lgkmcnt(" #n ")" ::: "memory")
; #define PG8_BAR __builtin_amdgcn_s_barrier()
; template <class Epi, class Sched, bool ALIGN_EPI = false, bool SP2 = false>
; __device__ __forceinline__ void gemm_phase(PG8_LAS unsigned char* lds, const Gemm g, const Sched& S, const Epi& E, const int wid_in) {
;     ...
;         for (int t = 0; t < nt; t += 2) {
;             const bool last = (t == nt - 2);
;             const char* a1 = cA + (size_t)(t + 1) * kstep;
;             const char* a2 = last ? nA : cA + (size_t)(t + 2) * kstep; const char* b2 = last ? nB : cB + (size_t)(t + 2) * kstep;
;             const char* a3 = a2 + kstep; const char* b3 = b2 + kstep;
;             if (last && has_next) S.a_ready(nxt);
;             if constexpr (SP2) {
;             PG8_LDB(B0, 0, 0); PG8_LDB(B1, 0, 1); PG8_SCHED; PG8_LDA(At, 0, 0); PG8_STAGE(PG8_SA(1, 1), a1 + hstep, voffA);
;             PG8_WAIT_V(8); PG8_WAIT_L(0); PG8_BAR; PG8_MMA(0, 0, At, B0); PG8_MMA(0, 1, At, B1); PG8_BAR; PG8_SCHED;
;             PG8_LDA(At, 0, 1); PG8_STAGE(PG8_SB(0, 0), b2, voffB); PG8_STAGE(PG8_SB(0, 1), b2 + hstep, voffB); PG8_STAGE(PG8_SA(0, 0), a2, voffA);
.LBB0_133:
	s_add_u32 s6, s4, 0xfff80080
	s_addc_u32 s7, s5, -1
	s_add_i32 s45, 0, 0x10000
	s_cmp_eq_u32 s44, 28
	s_cselect_b32 s25, s19, s7
	s_cselect_b32 s24, s40, s6
	s_cselect_b32 s7, s17, s43
	s_cselect_b32 s6, s41, s42
	s_add_i32 s48, 0, 0x14000
.Lrot_h_133:
	v_add_u32_e32 v142, s45, v147
	ds_read_b128 v[138:141], v142
	ds_read_b128 v[150:153], v142 offset:1024
	ds_read_b128 v[154:157], v142 offset:2048
	ds_read_b128 v[158:161], v142 offset:3072
	v_add_u32_e32 v142, s48, v147
	ds_read_b128 v[162:165], v142
	ds_read_b128 v[166:169], v142 offset:1024
	ds_read_b128 v[170:173], v142 offset:2048
	ds_read_b128 v[174:177], v142 offset:3072
	v_lshl_add_u64 v[142:143], s[4:5], 0, v[134:135]
	s_add_i32 m0, s29, 0xc000
	ds_read_b128 v[178:181], v149
	ds_read_b128 v[190:193], v149 offset:1024
	ds_read_b128 v[194:197], v149 offset:2048
	ds_read_b128 v[198:201], v149 offset:3072
	ds_read_b128 v[202:205], v149 offset:4096
	ds_read_b128 v[214:217], v149 offset:5120
	ds_read_b128 v[218:221], v149 offset:6144
	ds_read_b128 v[222:225], v149 offset:7168
	global_load_lds_dwordx4 v[142:143], off
	v_lshl_add_u64 v[142:143], s[4:5], 0, v[136:137]
	s_add_i32 m0, s29, 0xe000
	s_nop 0
	global_load_lds_dwordx4 v[142:143], off
	s_waitcnt vmcnt(8)
	s_waitcnt lgkmcnt(0)
	s_barrier
	s_setprio 1
	s_waitcnt lgkmcnt(0)
	v_mfma_f32_16x16x32_bf16 v[124:127], v[138:141], v[178:181], v[124:127]
	v_mfma_f32_16x16x32_bf16 v[120:123], v[154:157], v[178:181], v[120:123]
	v_mfma_f32_16x16x32_bf16 v[108:111], v[138:141], v[194:197], v[108:111]
	v_mfma_f32_16x16x32_bf16 v[104:107], v[154:157], v[194:197], v[104:107]
	v_mfma_f32_16x16x32_bf16 v[92:95], v[138:141], v[202:205], v[92:95]
	v_mfma_f32_16x16x32_bf16 v[88:91], v[154:157], v[202:205], v[88:91]
	v_mfma_f32_16x16x32_bf16 v[76:79], v[138:141], v[218:221], v[76:79]
	v_mfma_f32_16x16x32_bf16 v[72:75], v[154:157], v[218:221], v[72:75]
	v_mfma_f32_16x16x32_bf16 v[124:127], v[150:153], v[190:193], v[124:127]
	v_mfma_f32_16x16x32_bf16 v[120:123], v[158:161], v[190:193], v[120:123]
	v_mfma_f32_16x16x32_bf16 v[108:111], v[150:153], v[198:201], v[108:111]
	v_mfma_f32_16x16x32_bf16 v[104:107], v[158:161], v[198:201], v[104:107]
	v_mfma_f32_16x16x32_bf16 v[92:95], v[150:153], v[214:217], v[92:95]
	v_mfma_f32_16x16x32_bf16 v[88:91], v[158:161], v[214:217], v[88:91]
	v_mfma_f32_16x16x32_bf16 v[76:79], v[150:153], v[222:225], v[76:79]
	v_mfma_f32_16x16x32_bf16 v[72:75], v[158:161], v[222:225], v[72:75]
	s_setprio 0
	s_setprio 1
	v_mfma_f32_16x16x32_bf16 v[116:119], v[162:165], v[178:181], v[116:119]
	v_mfma_f32_16x16x32_bf16 v[112:115], v[170:173], v[178:181], v[112:115]
	v_mfma_f32_16x16x32_bf16 v[100:103], v[162:165], v[194:197], v[100:103]
	v_mfma_f32_16x16x32_bf16 v[96:99], v[170:173], v[194:197], v[96:99]
	v_mfma_f32_16x16x32_bf16 v[84:87], v[162:165], v[202:205], v[84:87]
	v_mfma_f32_16x16x32_bf16 v[80:83], v[170:173], v[202:205], v[80:83]
	v_mfma_f32_16x16x32_bf16 v[68:71], v[162:165], v[218:221], v[68:71]
	v_mfma_f32_16x16x32_bf16 v[64:67], v[170:173], v[218:221], v[64:67]
	v_mfma_f32_16x16x32_bf16 v[116:119], v[166:169], v[190:193], v[116:119]
	v_mfma_f32_16x16x32_bf16 v[112:115], v[174:177], v[190:193], v[112:115]
	v_mfma_f32_16x16x32_bf16 v[100:103], v[166:169], v[198:201], v[100:103]
	v_mfma_f32_16x16x32_bf16 v[96:99], v[174:177], v[198:201], v[96:99]
	v_mfma_f32_16x16x32_bf16 v[84:87], v[166:169], v[214:217], v[84:87]
	v_mfma_f32_16x16x32_bf16 v[80:83], v[174:177], v[214:217], v[80:83]
	v_mfma_f32_16x16x32_bf16 v[68:71], v[166:169], v[222:225], v[68:71]
	v_mfma_f32_16x16x32_bf16 v[64:67], v[174:177], v[222:225], v[64:67]
	s_setprio 0
	s_barrier
	s_add_i32 s45, s45, s28
	v_lshl_add_u64 v[142:143], s[6:7], 0, v[182:183]
	s_mov_b32 m0, s45
	ds_read_b128 v[178:181], v149 offset:16384
	ds_read_b128 v[190:193], v149 offset:17408
	ds_read_b128 v[194:197], v149 offset:18432
	ds_read_b128 v[198:201], v149 offset:19456
	ds_read_b128 v[202:205], v149 offset:20480
	ds_read_b128 v[214:217], v149 offset:21504
	ds_read_b128 v[218:221], v149 offset:22528
	ds_read_b128 v[222:225], v149 offset:23552
	global_load_lds_dwordx4 v[142:143], off
	s_add_i32 m0, s45, 0x2000
	s_add_u32 s46, s6, 0x80000
	v_lshl_add_u64 v[188:189], s[6:7], 0, v[128:129]
	s_addc_u32 s47, s7, 0
	s_add_i32 s45, s48, s28
	global_load_lds_dwordx4 v[188:189], off
	v_lshl_add_u64 v[226:227], s[46:47], 0, v[182:183]
	s_mov_b32 m0, s45
	v_lshl_add_u64 v[228:229], s[24:25], 0, v[130:131]
	global_load_lds_dwordx4 v[226:227], off
	v_lshl_add_u64 v[226:227], s[46:47], 0, v[128:129]
	s_add_i32 m0, s45, 0x2000
	s_nop 0
	global_load_lds_dwordx4 v[226:227], off
	v_lshl_add_u64 v[226:227], s[24:25], 0, v[132:133]
	s_mov_b32 m0, s29
	s_nop 0
	global_load_lds_dwordx4 v[226:227], off
	s_mov_b32 m0, s30
	s_nop 0
	global_load_lds_dwordx4 v[228:229], off
	s_waitcnt vmcnt(8)
	s_waitcnt lgkmcnt(0)
	s_barrier
; #define PG8_STAGE(bufoff, gbase, voff) do { _Pragma("unroll") for (int _i = 0; _i < 2; ++_i) \
;         __builtin_amdgcn_global_load_lds((const unsigned*)((const char*)(gbase) + (voff)[_i]), (PG8_LAS unsigned*)(lds + (bufoff) + ldsw + _i * 8192), 16, 0, 0); } while (0)
; #define PG8_LDA(dst, b, h) do { _Pragma("unroll") for (int m = 0; m < 4; ++m) _Pragma("unroll") for (int k = 0; k < 2; ++k) dst[m][k] = *(const PG8_LAS bf16x8*)(lds + PG8_SA(b, h) + aoff + m * 2048 + k * 1024); } while (0)
; #define PG8_LDB(dst, b, h) do { _Pragma("unroll") for (int n = 0; n < 2; ++n) _Pragma("unroll") for (int k = 0; k < 2; ++k) dst[n][k] = *(const PG8_LAS bf16x8*)(lds + PG8_SB(b, h) + boff + n * 2048 + k * 1024); } while (0)
; #define PG8_MMA(ai, bj, At, Bt) do { __builtin_amdgcn_s_setprio(1); _Pragma("unroll") for (int m = 0; m < 4; ++m) _Pragma("unroll") for (int n = 0; n < 2; ++n) _Pragma("unroll") for (int k = 0; k < 2; ++k) \
;         acc[ai][bj][m][n] = __builtin_amdgcn_mfma_f32_16x16x32_bf16(Bt[n][k], At[m][k], acc[ai][bj][m][n], 0, 0, 0); __builtin_amdgcn_s_setprio(0); } while (0)
; #define PG8_WAIT_V(n) asm volatile("s_waitcnt vmcnt(" #n ")" ::: "memory")
; #define PG8_WAIT_L(n) asm volatile("s_waitcnt lgkmcnt(" #n ")" ::: "memory")
; #define PG8_BAR __builtin_amdgcn_s_barrier()
; #define PG8_SCHED __builtin_amdgcn_sched_barrier(0)
; template <class Epi, class Sched, bool ALIGN_EPI = false, bool SP2 = false>
; __device__ __forceinline__ void gemm_phase(PG8_LAS unsigned char* lds, const Gemm g, const Sched& S, const Epi& E, const int wid_in) {
;     ...
;             PG8_WAIT_V(8); PG8_WAIT_L(0); PG8_BAR; PG8_MMA(1, 0, At, B0); PG8_MMA(1, 1, At, B1); PG8_BAR; PG8_SCHED;
;             PG8_LDB(B0, 1, 0); PG8_LDB(B1, 1, 1); PG8_SCHED; PG8_LDA(At, 1, 0); PG8_STAGE(PG8_SA(0, 1), a2 + hstep, voffA);
;             PG8_WAIT_V(8); PG8_WAIT_L(0); PG8_BAR; PG8_MMA(0, 0, At, B0); PG8_MMA(0, 1, At, B1); PG8_BAR; PG8_SCHED;
	s_setprio 1
	s_waitcnt lgkmcnt(0)
	v_mfma_f32_16x16x32_bf16 v[60:63], v[138:141], v[178:181], v[60:63]
	v_mfma_f32_16x16x32_bf16 v[56:59], v[154:157], v[178:181], v[56:59]
	v_mfma_f32_16x16x32_bf16 v[44:47], v[138:141], v[194:197], v[44:47]
	v_mfma_f32_16x16x32_bf16 v[40:43], v[154:157], v[194:197], v[40:43]
	v_mfma_f32_16x16x32_bf16 v[28:31], v[138:141], v[202:205], v[28:31]
	v_mfma_f32_16x16x32_bf16 v[24:27], v[154:157], v[202:205], v[24:27]
	v_mfma_f32_16x16x32_bf16 v[12:15], v[138:141], v[218:221], v[12:15]
	v_mfma_f32_16x16x32_bf16 v[8:11], v[154:157], v[218:221], v[8:11]
	v_mfma_f32_16x16x32_bf16 v[60:63], v[150:153], v[190:193], v[60:63]
	v_mfma_f32_16x16x32_bf16 v[56:59], v[158:161], v[190:193], v[56:59]
	v_mfma_f32_16x16x32_bf16 v[44:47], v[150:153], v[198:201], v[44:47]
	v_mfma_f32_16x16x32_bf16 v[40:43], v[158:161], v[198:201], v[40:43]
	v_mfma_f32_16x16x32_bf16 v[28:31], v[150:153], v[214:217], v[28:31]
	v_mfma_f32_16x16x32_bf16 v[24:27], v[158:161], v[214:217], v[24:27]
	v_mfma_f32_16x16x32_bf16 v[12:15], v[150:153], v[222:225], v[12:15]
	v_mfma_f32_16x16x32_bf16 v[8:11], v[158:161], v[222:225], v[8:11]
	s_setprio 0
	s_setprio 1
	v_mfma_f32_16x16x32_bf16 v[52:55], v[162:165], v[178:181], v[52:55]
	v_mfma_f32_16x16x32_bf16 v[48:51], v[170:173], v[178:181], v[48:51]
	v_mfma_f32_16x16x32_bf16 v[36:39], v[162:165], v[194:197], v[36:39]
	v_mfma_f32_16x16x32_bf16 v[32:35], v[170:173], v[194:197], v[32:35]
	v_mfma_f32_16x16x32_bf16 v[20:23], v[162:165], v[202:205], v[20:23]
	v_mfma_f32_16x16x32_bf16 v[16:19], v[170:173], v[202:205], v[16:19]
	v_mfma_f32_16x16x32_bf16 v[4:7], v[162:165], v[218:221], v[4:7]
	v_mfma_f32_16x16x32_bf16 v[0:3], v[170:173], v[218:221], v[0:3]
	v_mfma_f32_16x16x32_bf16 v[52:55], v[166:169], v[190:193], v[52:55]
	v_mfma_f32_16x16x32_bf16 v[48:51], v[174:177], v[190:193], v[48:51]
	v_mfma_f32_16x16x32_bf16 v[36:39], v[166:169], v[198:201], v[36:39]
	v_mfma_f32_16x16x32_bf16 v[32:35], v[174:177], v[198:201], v[32:35]
	v_mfma_f32_16x16x32_bf16 v[20:23], v[166:169], v[214:217], v[20:23]
	v_mfma_f32_16x16x32_bf16 v[16:19], v[174:177], v[214:217], v[16:19]
	v_mfma_f32_16x16x32_bf16 v[4:7], v[166:169], v[222:225], v[4:7]
	v_mfma_f32_16x16x32_bf16 v[0:3], v[174:177], v[222:225], v[0:3]
	s_setprio 0
	s_barrier
	s_add_i32 s45, 0, 0x18000
	v_add_u32_e32 v144, s45, v147
	s_add_i32 s46, 0, 0x1c000
	ds_read_b128 v[138:141], v144
	ds_read_b128 v[150:153], v144 offset:1024
	ds_read_b128 v[154:157], v144 offset:2048
	ds_read_b128 v[158:161], v144 offset:3072
	v_add_u32_e32 v144, s46, v147
	ds_read_b128 v[162:165], v144
	ds_read_b128 v[166:169], v144 offset:1024
	ds_read_b128 v[170:173], v144 offset:2048
	ds_read_b128 v[174:177], v144 offset:3072
	s_add_u32 s24, s24, 0x80000
	s_addc_u32 s25, s25, 0
	s_mov_b32 m0, s31
	v_lshl_add_u64 v[230:231], s[24:25], 0, v[132:133]
	ds_read_b128 v[178:181], v149 offset:32768
	ds_read_b128 v[190:193], v149 offset:33792
	ds_read_b128 v[194:197], v149 offset:34816
	ds_read_b128 v[198:201], v149 offset:35840
	ds_read_b128 v[202:205], v149 offset:36864
	ds_read_b128 v[214:217], v149 offset:37888
	ds_read_b128 v[218:221], v149 offset:38912
	ds_read_b128 v[222:225], v149 offset:39936
	global_load_lds_dwordx4 v[230:231], off
	v_lshl_add_u64 v[230:231], s[24:25], 0, v[130:131]
	s_mov_b32 m0, s34
	s_nop 0
	global_load_lds_dwordx4 v[230:231], off
	s_waitcnt vmcnt(8)
	s_waitcnt lgkmcnt(0)
	s_barrier
	s_setprio 1
	s_waitcnt lgkmcnt(0)
	v_mfma_f32_16x16x32_bf16 v[124:127], v[138:141], v[178:181], v[124:127]
	v_mfma_f32_16x16x32_bf16 v[120:123], v[154:157], v[178:181], v[120:123]
	v_mfma_f32_16x16x32_bf16 v[108:111], v[138:141], v[194:197], v[108:111]
	v_mfma_f32_16x16x32_bf16 v[104:107], v[154:157], v[194:197], v[104:107]
	v_mfma_f32_16x16x32_bf16 v[92:95], v[138:141], v[202:205], v[92:95]
	v_mfma_f32_16x16x32_bf16 v[88:91], v[154:157], v[202:205], v[88:91]
	v_mfma_f32_16x16x32_bf16 v[76:79], v[138:141], v[218:221], v[76:79]
	v_mfma_f32_16x16x32_bf16 v[72:75], v[154:157], v[218:221], v[72:75]
	v_mfma_f32_16x16x32_bf16 v[124:127], v[150:153], v[190:193], v[124:127]
	v_mfma_f32_16x16x32_bf16 v[120:123], v[158:161], v[190:193], v[120:123]
	v_mfma_f32_16x16x32_bf16 v[108:111], v[150:153], v[198:201], v[108:111]
	v_mfma_f32_16x16x32_bf16 v[104:107], v[158:161], v[198:201], v[104:107]
	v_mfma_f32_16x16x32_bf16 v[92:95], v[150:153], v[214:217], v[92:95]
	v_mfma_f32_16x16x32_bf16 v[88:91], v[158:161], v[214:217], v[88:91]
	v_mfma_f32_16x16x32_bf16 v[76:79], v[150:153], v[222:225], v[76:79]
	v_mfma_f32_16x16x32_bf16 v[72:75], v[158:161], v[222:225], v[72:75]
	s_setprio 0
	s_setprio 1
	v_mfma_f32_16x16x32_bf16 v[116:119], v[162:165], v[178:181], v[116:119]
	v_mfma_f32_16x16x32_bf16 v[112:115], v[170:173], v[178:181], v[112:115]
	v_mfma_f32_16x16x32_bf16 v[100:103], v[162:165], v[194:197], v[100:103]
	v_mfma_f32_16x16x32_bf16 v[96:99], v[170:173], v[194:197], v[96:99]
	v_mfma_f32_16x16x32_bf16 v[84:87], v[162:165], v[202:205], v[84:87]
	v_mfma_f32_16x16x32_bf16 v[80:83], v[170:173], v[202:205], v[80:83]
	v_mfma_f32_16x16x32_bf16 v[68:71], v[162:165], v[218:221], v[68:71]
	v_mfma_f32_16x16x32_bf16 v[64:67], v[170:173], v[218:221], v[64:67]
	v_mfma_f32_16x16x32_bf16 v[116:119], v[166:169], v[190:193], v[116:119]
	v_mfma_f32_16x16x32_bf16 v[112:115], v[174:177], v[190:193], v[112:115]
	v_mfma_f32_16x16x32_bf16 v[100:103], v[166:169], v[198:201], v[100:103]
	v_mfma_f32_16x16x32_bf16 v[96:99], v[174:177], v[198:201], v[96:99]
	v_mfma_f32_16x16x32_bf16 v[84:87], v[166:169], v[214:217], v[84:87]
	v_mfma_f32_16x16x32_bf16 v[80:83], v[174:177], v[214:217], v[80:83]
	v_mfma_f32_16x16x32_bf16 v[68:71], v[166:169], v[222:225], v[68:71]
	v_mfma_f32_16x16x32_bf16 v[64:67], v[174:177], v[222:225], v[64:67]
	s_setprio 0
	s_barrier
; #define PG8_STAGE(bufoff, gbase, voff) do { _Pragma("unroll") for (int _i = 0; _i < 2; ++_i) \
;         __builtin_amdgcn_global_load_lds((const unsigned*)((const char*)(gbase) + (voff)[_i]), (PG8_LAS unsigned*)(lds + (bufoff) + ldsw + _i * 8192), 16, 0, 0); } while (0)
; #define PG8_LDA(dst, b, h) do { _Pragma("unroll") for (int m = 0; m < 4; ++m) _Pragma("unroll") for (int k = 0; k < 2; ++k) dst[m][k] = *(const PG8_LAS bf16x8*)(lds + PG8_SA(b, h) + aoff + m * 2048 + k * 1024); } while (0)
; #define PG8_MMA(ai, bj, At, Bt) do { __builtin_amdgcn_s_setprio(1); _Pragma("unroll") for (int m = 0; m < 4; ++m) _Pragma("unroll") for (int n = 0; n < 2; ++n) _Pragma("unroll") for (int k = 0; k < 2; ++k) \
;         acc[ai][bj][m][n] = __builtin_amdgcn_mfma_f32_16x16x32_bf16(Bt[n][k], At[m][k], acc[ai][bj][m][n], 0, 0, 0); __builtin_amdgcn_s_setprio(0); } while (0)
; #define PG8_WAIT_V(n) asm volatile("s_waitcnt vmcnt(" #n ")" ::: "memory")
; #define PG8_WAIT_L(n) asm volatile("s_waitcnt lgkmcnt(" #n ")" ::: "memory")
; #define PG8_BAR __builtin_amdgcn_s_barrier()
; #define PG8_SCHED __builtin_amdgcn_sched_barrier(0)
; template <class Epi, class Sched, bool ALIGN_EPI = false, bool SP2 = false>
; __device__ __forceinline__ void gemm_phase(PG8_LAS unsigned char* lds, const Gemm g, const Sched& S, const Epi& E, const int wid_in) {
;     ...
;         for (int t = 0; t < nt; t += 2) {
;             const bool last = (t == nt - 2);
;             const char* a1 = cA + (size_t)(t + 1) * kstep;
;             const char* a2 = last ? nA : cA + (size_t)(t + 2) * kstep; const char* b2 = last ? nB : cB + (size_t)(t + 2) * kstep;
;             const char* a3 = a2 + kstep; const char* b3 = b2 + kstep;
;             if (last && has_next) S.a_ready(nxt);
;     ...
;             PG8_LDA(At, 1, 1); PG8_STAGE(PG8_SB(1, 0), b3, voffB); PG8_STAGE(PG8_SB(1, 1), b3 + hstep, voffB); PG8_STAGE(PG8_SA(1, 0), a3, voffA);
;             PG8_WAIT_V(8); PG8_WAIT_L(0); PG8_BAR; PG8_MMA(1, 0, At, B0); PG8_MMA(1, 1, At, B1); PG8_BAR; PG8_SCHED;
	s_add_i32 s24, s45, s28
	v_lshl_add_u64 v[142:143], v[142:143], 0, s[74:75]
	s_mov_b32 m0, s24
	ds_read_b128 v[178:181], v149 offset:49152
	ds_read_b128 v[190:193], v149 offset:50176
	ds_read_b128 v[194:197], v149 offset:51200
	ds_read_b128 v[198:201], v149 offset:52224
	ds_read_b128 v[202:205], v149 offset:53248
	ds_read_b128 v[214:217], v149 offset:54272
	ds_read_b128 v[218:221], v149 offset:55296
	ds_read_b128 v[222:225], v149 offset:56320
	global_load_lds_dwordx4 v[142:143], off
	s_add_i32 m0, s24, 0x2000
	s_add_u32 s6, s6, 0x80080
	v_lshl_add_u64 v[142:143], v[188:189], 0, s[74:75]
	s_addc_u32 s7, s7, 0
	s_add_i32 s24, s46, s28
	global_load_lds_dwordx4 v[142:143], off
	v_lshl_add_u64 v[142:143], s[6:7], 0, v[182:183]
	s_mov_b32 m0, s24
	s_nop 0
	global_load_lds_dwordx4 v[142:143], off
	v_lshl_add_u64 v[142:143], s[6:7], 0, v[128:129]
	s_add_i32 m0, s24, 0x2000
	s_nop 0
	global_load_lds_dwordx4 v[142:143], off
	v_lshl_add_u64 v[142:143], v[226:227], 0, s[74:75]
	s_mov_b32 m0, s35
	s_nop 0
	global_load_lds_dwordx4 v[142:143], off
	v_lshl_add_u64 v[142:143], v[228:229], 0, s[74:75]
	s_mov_b32 m0, s36
	s_nop 0
	global_load_lds_dwordx4 v[142:143], off
	s_waitcnt vmcnt(8)
	s_waitcnt lgkmcnt(0)
	s_barrier
	s_setprio 1
	s_waitcnt lgkmcnt(0)
	v_mfma_f32_16x16x32_bf16 v[60:63], v[138:141], v[178:181], v[60:63]
	v_mfma_f32_16x16x32_bf16 v[56:59], v[154:157], v[178:181], v[56:59]
	v_mfma_f32_16x16x32_bf16 v[44:47], v[138:141], v[194:197], v[44:47]
	v_mfma_f32_16x16x32_bf16 v[40:43], v[154:157], v[194:197], v[40:43]
	v_mfma_f32_16x16x32_bf16 v[28:31], v[138:141], v[202:205], v[28:31]
	v_mfma_f32_16x16x32_bf16 v[24:27], v[154:157], v[202:205], v[24:27]
	v_mfma_f32_16x16x32_bf16 v[12:15], v[138:141], v[218:221], v[12:15]
	v_mfma_f32_16x16x32_bf16 v[8:11], v[154:157], v[218:221], v[8:11]
	v_mfma_f32_16x16x32_bf16 v[60:63], v[150:153], v[190:193], v[60:63]
	v_mfma_f32_16x16x32_bf16 v[56:59], v[158:161], v[190:193], v[56:59]
	v_mfma_f32_16x16x32_bf16 v[44:47], v[150:153], v[198:201], v[44:47]
	v_mfma_f32_16x16x32_bf16 v[40:43], v[158:161], v[198:201], v[40:43]
	v_mfma_f32_16x16x32_bf16 v[28:31], v[150:153], v[214:217], v[28:31]
	v_mfma_f32_16x16x32_bf16 v[24:27], v[158:161], v[214:217], v[24:27]
	v_mfma_f32_16x16x32_bf16 v[12:15], v[150:153], v[222:225], v[12:15]
	v_mfma_f32_16x16x32_bf16 v[8:11], v[158:161], v[222:225], v[8:11]
	s_setprio 0
	s_setprio 1
	v_mfma_f32_16x16x32_bf16 v[52:55], v[162:165], v[178:181], v[52:55]
	v_mfma_f32_16x16x32_bf16 v[48:51], v[170:173], v[178:181], v[48:51]
	v_mfma_f32_16x16x32_bf16 v[36:39], v[162:165], v[194:197], v[36:39]
	v_mfma_f32_16x16x32_bf16 v[32:35], v[170:173], v[194:197], v[32:35]
	v_mfma_f32_16x16x32_bf16 v[20:23], v[162:165], v[202:205], v[20:23]
	v_mfma_f32_16x16x32_bf16 v[16:19], v[170:173], v[202:205], v[16:19]
	v_mfma_f32_16x16x32_bf16 v[4:7], v[162:165], v[218:221], v[4:7]
	v_mfma_f32_16x16x32_bf16 v[0:3], v[170:173], v[218:221], v[0:3]
	v_mfma_f32_16x16x32_bf16 v[52:55], v[166:169], v[190:193], v[52:55]
	v_mfma_f32_16x16x32_bf16 v[48:51], v[174:177], v[190:193], v[48:51]
	v_mfma_f32_16x16x32_bf16 v[36:39], v[166:169], v[198:201], v[36:39]
	v_mfma_f32_16x16x32_bf16 v[32:35], v[174:177], v[198:201], v[32:35]
	v_mfma_f32_16x16x32_bf16 v[20:23], v[166:169], v[214:217], v[20:23]
	v_mfma_f32_16x16x32_bf16 v[16:19], v[174:177], v[214:217], v[16:19]
	v_mfma_f32_16x16x32_bf16 v[4:7], v[166:169], v[222:225], v[4:7]
	v_mfma_f32_16x16x32_bf16 v[0:3], v[174:177], v[222:225], v[0:3]
	s_setprio 0
	s_add_i32 s44, s44, 2
	s_add_u32 s4, s4, 0x100
	s_addc_u32 s5, s5, 0
	s_add_u32 s42, s42, 0x100
	s_addc_u32 s43, s43, 0
	s_cmp_gt_u32 s44, 29
	s_cbranch_scc1 .Lrot_x_133
	s_add_u32 s6, s4, 0xfff80080
	s_addc_u32 s7, s5, -1
	s_add_i32 s45, 0, 0x10000
	s_cmp_eq_u32 s44, 28
	s_cselect_b32 s25, s19, s7
	s_cselect_b32 s24, s40, s6
	s_cselect_b32 s7, s17, s43
	s_cselect_b32 s6, s41, s42
	s_add_i32 s48, 0, 0x14000
	s_barrier
	s_branch .Lrot_h_133
.Lrot_x_133:
	s_barrier
	s_and_b64 vcc, exec, s[14:15]
	s_cbranch_vccz .LBB0_136
	s_barrier

; #define PG8_STAGE(bufoff, gbase, voff) do { _Pragma("unroll") for (int _i = 0; _i < 2; ++_i) \
;         __builtin_amdgcn_global_load_lds((const unsigned*)((const char*)(gbase) + (voff)[_i]), (PG8_LAS unsigned*)(lds + (bufoff) + ldsw + _i * 8192), 16, 0, 0); } while (0)
; #define PG8_LDA(dst, b, h) do { _Pragma("unroll") for (int m = 0; m < 4; ++m) _Pragma("unroll") for (int k = 0; k < 2; ++k) dst[m][k] = *(const PG8_LAS bf16x8*)(lds + PG8_SA(b, h) + aoff + m * 2048 + k * 1024); } while (0)
; #define PG8_LDB(dst, b, h) do { _Pragma("unroll") for (int n = 0; n < 2; ++n) _Pragma("unroll") for (int k = 0; k < 2; ++k) dst[n][k] = *(const PG8_LAS bf16x8*)(lds + PG8_SB(b, h) + boff + n * 2048 + k * 1024); } while (0)
; #define PG8_MMA(ai, bj, At, Bt) do { __builtin_amdgcn_s_setprio(1); _Pragma("unroll") for (int m = 0; m < 4; ++m) _Pragma("unroll") for (int n = 0; n < 2; ++n) _Pragma("unroll") for (int k = 0; k < 2; ++k) \
;         acc[ai][bj][m][n] = __builtin_amdgcn_mfma_f32_16x16x32_bf16(Bt[n][k], At[m][k], acc[ai][bj][m][n], 0, 0, 0); __builtin_amdgcn_s_setprio(0); } while (0)
; #define PG8_WAIT_V(n) asm volatile("s_waitcnt vmcnt(" #n ")" ::: "memory")
; #define PG8_WAIT_L(n) asm volatile("s_waitcnt lgkmcnt(" #n ")" ::: "memory")
; #define PG8_BAR __builtin_amdgcn_s_barrier()
; template <class Epi, class Sched, bool ALIGN_EPI = false, bool SP2 = false>
; __device__ __forceinline__ void gemm_phase(PG8_LAS unsigned char* lds, const Gemm g, const Sched& S, const Epi& E, const int wid_in) {
;     ...
;         for (int t = 0; t < nt; t += 2) {
;             const bool last = (t == nt - 2);
;             const char* a1 = cA + (size_t)(t + 1) * kstep;
;             const char* a2 = last ? nA : cA + (size_t)(t + 2) * kstep; const char* b2 = last ? nB : cB + (size_t)(t + 2) * kstep;
;             const char* a3 = a2 + kstep; const char* b3 = b2 + kstep;
;             if (last && has_next) S.a_ready(nxt);
;             if constexpr (SP2) {
;             PG8_LDB(B0, 0, 0); PG8_LDB(B1, 0, 1); PG8_SCHED; PG8_LDA(At, 0, 0); PG8_STAGE(PG8_SA(1, 1), a1 + hstep, voffA);
;             PG8_WAIT_V(8); PG8_WAIT_L(0); PG8_BAR; PG8_MMA(0, 0, At, B0); PG8_MMA(0, 1, At, B1); PG8_BAR; PG8_SCHED;
;             PG8_LDA(At, 0, 1); PG8_STAGE(PG8_SB(0, 0), b2, voffB); PG8_STAGE(PG8_SB(0, 1), b2 + hstep, voffB); PG8_STAGE(PG8_SA(0, 0), a2, voffA);
.Lrot_h_167:
	v_add_u32_e32 v138, s45, v147
	ds_read_b128 v[140:143], v138
	ds_read_b128 v[150:153], v138 offset:1024
	ds_read_b128 v[154:157], v138 offset:2048
	ds_read_b128 v[158:161], v138 offset:3072
	v_add_u32_e32 v138, s48, v147
	ds_read_b128 v[162:165], v138
	ds_read_b128 v[166:169], v138 offset:1024
	ds_read_b128 v[170:173], v138 offset:2048
	ds_read_b128 v[174:177], v138 offset:3072
	v_lshl_add_u64 v[144:145], s[4:5], 0, v[134:135]
	s_add_i32 m0, s29, 0xc000
	ds_read_b128 v[178:181], v149
	ds_read_b128 v[190:193], v149 offset:1024
	ds_read_b128 v[194:197], v149 offset:2048
	ds_read_b128 v[198:201], v149 offset:3072
	ds_read_b128 v[202:205], v149 offset:4096
	ds_read_b128 v[214:217], v149 offset:5120
	ds_read_b128 v[218:221], v149 offset:6144
	ds_read_b128 v[222:225], v149 offset:7168
	global_load_lds_dwordx4 v[144:145], off
	v_lshl_add_u64 v[144:145], s[4:5], 0, v[136:137]
	s_add_i32 m0, s29, 0xe000
	s_nop 0
	global_load_lds_dwordx4 v[144:145], off
	s_waitcnt vmcnt(8)
	s_waitcnt lgkmcnt(0)
	s_barrier
	s_setprio 1
	s_waitcnt lgkmcnt(0)
	v_mfma_f32_16x16x32_bf16 v[124:127], v[140:143], v[178:181], v[124:127]
	v_mfma_f32_16x16x32_bf16 v[120:123], v[154:157], v[178:181], v[120:123]
	v_mfma_f32_16x16x32_bf16 v[108:111], v[140:143], v[194:197], v[108:111]
	v_mfma_f32_16x16x32_bf16 v[104:107], v[154:157], v[194:197], v[104:107]
	v_mfma_f32_16x16x32_bf16 v[92:95], v[140:143], v[202:205], v[92:95]
	v_mfma_f32_16x16x32_bf16 v[88:91], v[154:157], v[202:205], v[88:91]
	v_mfma_f32_16x16x32_bf16 v[76:79], v[140:143], v[218:221], v[76:79]
	v_mfma_f32_16x16x32_bf16 v[72:75], v[154:157], v[218:221], v[72:75]
	v_mfma_f32_16x16x32_bf16 v[124:127], v[150:153], v[190:193], v[124:127]
	v_mfma_f32_16x16x32_bf16 v[120:123], v[158:161], v[190:193], v[120:123]
	v_mfma_f32_16x16x32_bf16 v[108:111], v[150:153], v[198:201], v[108:111]
	v_mfma_f32_16x16x32_bf16 v[104:107], v[158:161], v[198:201], v[104:107]
	v_mfma_f32_16x16x32_bf16 v[92:95], v[150:153], v[214:217], v[92:95]
	v_mfma_f32_16x16x32_bf16 v[88:91], v[158:161], v[214:217], v[88:91]
	v_mfma_f32_16x16x32_bf16 v[76:79], v[150:153], v[222:225], v[76:79]
	v_mfma_f32_16x16x32_bf16 v[72:75], v[158:161], v[222:225], v[72:75]
	s_setprio 0
	s_setprio 1
	v_mfma_f32_16x16x32_bf16 v[116:119], v[162:165], v[178:181], v[116:119]
	v_mfma_f32_16x16x32_bf16 v[112:115], v[170:173], v[178:181], v[112:115]
	v_mfma_f32_16x16x32_bf16 v[100:103], v[162:165], v[194:197], v[100:103]
	v_mfma_f32_16x16x32_bf16 v[96:99], v[170:173], v[194:197], v[96:99]
	v_mfma_f32_16x16x32_bf16 v[84:87], v[162:165], v[202:205], v[84:87]
	v_mfma_f32_16x16x32_bf16 v[80:83], v[170:173], v[202:205], v[80:83]
	v_mfma_f32_16x16x32_bf16 v[68:71], v[162:165], v[218:221], v[68:71]
	v_mfma_f32_16x16x32_bf16 v[64:67], v[170:173], v[218:221], v[64:67]
	v_mfma_f32_16x16x32_bf16 v[116:119], v[166:169], v[190:193], v[116:119]
	v_mfma_f32_16x16x32_bf16 v[112:115], v[174:177], v[190:193], v[112:115]
	v_mfma_f32_16x16x32_bf16 v[100:103], v[166:169], v[198:201], v[100:103]
	v_mfma_f32_16x16x32_bf16 v[96:99], v[174:177], v[198:201], v[96:99]
	v_mfma_f32_16x16x32_bf16 v[84:87], v[166:169], v[214:217], v[84:87]
	v_mfma_f32_16x16x32_bf16 v[80:83], v[174:177], v[214:217], v[80:83]
	v_mfma_f32_16x16x32_bf16 v[68:71], v[166:169], v[222:225], v[68:71]
	v_mfma_f32_16x16x32_bf16 v[64:67], v[174:177], v[222:225], v[64:67]
	s_setprio 0
	s_barrier
	s_add_i32 s45, s45, s28
	v_lshl_add_u64 v[144:145], s[6:7], 0, v[182:183]
	s_mov_b32 m0, s45
	ds_read_b128 v[178:181], v149 offset:16384
	ds_read_b128 v[190:193], v149 offset:17408
	ds_read_b128 v[194:197], v149 offset:18432
	ds_read_b128 v[198:201], v149 offset:19456
	ds_read_b128 v[202:205], v149 offset:20480
	ds_read_b128 v[214:217], v149 offset:21504
	ds_read_b128 v[218:221], v149 offset:22528
	ds_read_b128 v[222:225], v149 offset:23552
	global_load_lds_dwordx4 v[144:145], off
	s_add_i32 m0, s45, 0x2000
	s_add_u32 s46, s6, 0x80000
	v_lshl_add_u64 v[188:189], s[6:7], 0, v[128:129]
	s_addc_u32 s47, s7, 0
	s_add_i32 s45, s48, s28
	global_load_lds_dwordx4 v[188:189], off
	v_lshl_add_u64 v[226:227], s[46:47], 0, v[182:183]
	s_mov_b32 m0, s45
	v_lshl_add_u64 v[228:229], s[24:25], 0, v[130:131]
	global_load_lds_dwordx4 v[226:227], off
	v_lshl_add_u64 v[226:227], s[46:47], 0, v[128:129]
	s_add_i32 m0, s45, 0x2000
	s_nop 0
	global_load_lds_dwordx4 v[226:227], off
	v_lshl_add_u64 v[226:227], s[24:25], 0, v[132:133]
	s_mov_b32 m0, s29
	s_nop 0
	global_load_lds_dwordx4 v[226:227], off
	s_mov_b32 m0, s30
	s_nop 0
	global_load_lds_dwordx4 v[228:229], off
	s_waitcnt vmcnt(8)
	s_waitcnt lgkmcnt(0)
	s_barrier
; #define PG8_STAGE(bufoff, gbase, voff) do { _Pragma("unroll") for (int _i = 0; _i < 2; ++_i) \
;         __builtin_amdgcn_global_load_lds((const unsigned*)((const char*)(gbase) + (voff)[_i]), (PG8_LAS unsigned*)(lds + (bufoff) + ldsw + _i * 8192), 16, 0, 0); } while (0)
; #define PG8_LDA(dst, b, h) do { _Pragma("unroll") for (int m = 0; m < 4; ++m) _Pragma("unroll") for (int k = 0; k < 2; ++k) dst[m][k] = *(const PG8_LAS bf16x8*)(lds + PG8_SA(b, h) + aoff + m * 2048 + k * 1024); } while (0)
; #define PG8_LDB(dst, b, h) do { _Pragma("unroll") for (int n = 0; n < 2; ++n) _Pragma("unroll") for (int k = 0; k < 2; ++k) dst[n][k] = *(const PG8_LAS bf16x8*)(lds + PG8_SB(b, h) + boff + n * 2048 + k * 1024); } while (0)
; #define PG8_MMA(ai, bj, At, Bt) do { __builtin_amdgcn_s_setprio(1); _Pragma("unroll") for (int m = 0; m < 4; ++m) _Pragma("unroll") for (int n = 0; n < 2; ++n) _Pragma("unroll") for (int k = 0; k < 2; ++k) \
;         acc[ai][bj][m][n] = __builtin_amdgcn_mfma_f32_16x16x32_bf16(Bt[n][k], At[m][k], acc[ai][bj][m][n], 0, 0, 0); __builtin_amdgcn_s_setprio(0); } while (0)
; #define PG8_WAIT_V(n) asm volatile("s_waitcnt vmcnt(" #n ")" ::: "memory")
; #define PG8_WAIT_L(n) asm volatile("s_waitcnt lgkmcnt(" #n ")" ::: "memory")
; #define PG8_BAR __builtin_amdgcn_s_barrier()
; #define PG8_SCHED __builtin_amdgcn_sched_barrier(0)
; template <class Epi, class Sched, bool ALIGN_EPI = false, bool SP2 = false>
; __device__ __forceinline__ void gemm_phase(PG8_LAS unsigned char* lds, const Gemm g, const Sched& S, const Epi& E, const int wid_in) {
;     ...
;             PG8_WAIT_V(8); PG8_WAIT_L(0); PG8_BAR; PG8_MMA(1, 0, At, B0); PG8_MMA(1, 1, At, B1); PG8_BAR; PG8_SCHED;
;             PG8_LDB(B0, 1, 0); PG8_LDB(B1, 1, 1); PG8_SCHED; PG8_LDA(At, 1, 0); PG8_STAGE(PG8_SA(0, 1), a2 + hstep, voffA);
;             PG8_WAIT_V(8); PG8_WAIT_L(0); PG8_BAR; PG8_MMA(0, 0, At, B0); PG8_MMA(0, 1, At, B1); PG8_BAR; PG8_SCHED;
	s_setprio 1
	s_waitcnt lgkmcnt(0)
	v_mfma_f32_16x16x32_bf16 v[60:63], v[140:143], v[178:181], v[60:63]
	v_mfma_f32_16x16x32_bf16 v[56:59], v[154:157], v[178:181], v[56:59]
	v_mfma_f32_16x16x32_bf16 v[44:47], v[140:143], v[194:197], v[44:47]
	v_mfma_f32_16x16x32_bf16 v[40:43], v[154:157], v[194:197], v[40:43]
	v_mfma_f32_16x16x32_bf16 v[28:31], v[140:143], v[202:205], v[28:31]
	v_mfma_f32_16x16x32_bf16 v[24:27], v[154:157], v[202:205], v[24:27]
	v_mfma_f32_16x16x32_bf16 v[12:15], v[140:143], v[218:221], v[12:15]
	v_mfma_f32_16x16x32_bf16 v[8:11], v[154:157], v[218:221], v[8:11]
	v_mfma_f32_16x16x32_bf16 v[60:63], v[150:153], v[190:193], v[60:63]
	v_mfma_f32_16x16x32_bf16 v[56:59], v[158:161], v[190:193], v[56:59]
	v_mfma_f32_16x16x32_bf16 v[44:47], v[150:153], v[198:201], v[44:47]
	v_mfma_f32_16x16x32_bf16 v[40:43], v[158:161], v[198:201], v[40:43]
	v_mfma_f32_16x16x32_bf16 v[28:31], v[150:153], v[214:217], v[28:31]
	v_mfma_f32_16x16x32_bf16 v[24:27], v[158:161], v[214:217], v[24:27]
	v_mfma_f32_16x16x32_bf16 v[12:15], v[150:153], v[222:225], v[12:15]
	v_mfma_f32_16x16x32_bf16 v[8:11], v[158:161], v[222:225], v[8:11]
	s_setprio 0
	s_setprio 1
	v_mfma_f32_16x16x32_bf16 v[52:55], v[162:165], v[178:181], v[52:55]
	v_mfma_f32_16x16x32_bf16 v[48:51], v[170:173], v[178:181], v[48:51]
	v_mfma_f32_16x16x32_bf16 v[36:39], v[162:165], v[194:197], v[36:39]
	v_mfma_f32_16x16x32_bf16 v[32:35], v[170:173], v[194:197], v[32:35]
	v_mfma_f32_16x16x32_bf16 v[20:23], v[162:165], v[202:205], v[20:23]
	v_mfma_f32_16x16x32_bf16 v[16:19], v[170:173], v[202:205], v[16:19]
	v_mfma_f32_16x16x32_bf16 v[4:7], v[162:165], v[218:221], v[4:7]
	v_mfma_f32_16x16x32_bf16 v[0:3], v[170:173], v[218:221], v[0:3]
	v_mfma_f32_16x16x32_bf16 v[52:55], v[166:169], v[190:193], v[52:55]
	v_mfma_f32_16x16x32_bf16 v[48:51], v[174:177], v[190:193], v[48:51]
	v_mfma_f32_16x16x32_bf16 v[36:39], v[166:169], v[198:201], v[36:39]
	v_mfma_f32_16x16x32_bf16 v[32:35], v[174:177], v[198:201], v[32:35]
	v_mfma_f32_16x16x32_bf16 v[20:23], v[166:169], v[214:217], v[20:23]
	v_mfma_f32_16x16x32_bf16 v[16:19], v[174:177], v[214:217], v[16:19]
	v_mfma_f32_16x16x32_bf16 v[4:7], v[166:169], v[222:225], v[4:7]
	v_mfma_f32_16x16x32_bf16 v[0:3], v[174:177], v[222:225], v[0:3]
	s_setprio 0
	s_barrier
	s_add_i32 s45, 0, 0x18000
	v_add_u32_e32 v138, s45, v147
	s_add_i32 s46, 0, 0x1c000
	ds_read_b128 v[140:143], v138
	ds_read_b128 v[150:153], v138 offset:1024
	ds_read_b128 v[154:157], v138 offset:2048
	ds_read_b128 v[158:161], v138 offset:3072
	v_add_u32_e32 v138, s46, v147
	ds_read_b128 v[162:165], v138
	ds_read_b128 v[166:169], v138 offset:1024
	ds_read_b128 v[170:173], v138 offset:2048
	ds_read_b128 v[174:177], v138 offset:3072
	s_add_u32 s24, s24, 0x80000
	s_addc_u32 s25, s25, 0
	s_mov_b32 m0, s31
	v_lshl_add_u64 v[230:231], s[24:25], 0, v[132:133]
	ds_read_b128 v[178:181], v149 offset:32768
	ds_read_b128 v[190:193], v149 offset:33792
	ds_read_b128 v[194:197], v149 offset:34816
	ds_read_b128 v[198:201], v149 offset:35840
	ds_read_b128 v[202:205], v149 offset:36864
	ds_read_b128 v[214:217], v149 offset:37888
	ds_read_b128 v[218:221], v149 offset:38912
	ds_read_b128 v[222:225], v149 offset:39936
	global_load_lds_dwordx4 v[230:231], off
	v_lshl_add_u64 v[230:231], s[24:25], 0, v[130:131]
	s_mov_b32 m0, s34
	s_nop 0
	global_load_lds_dwordx4 v[230:231], off
	s_waitcnt vmcnt(8)
	s_waitcnt lgkmcnt(0)
	s_barrier
	s_setprio 1
	s_waitcnt lgkmcnt(0)
	v_mfma_f32_16x16x32_bf16 v[124:127], v[140:143], v[178:181], v[124:127]
	v_mfma_f32_16x16x32_bf16 v[120:123], v[154:157], v[178:181], v[120:123]
	v_mfma_f32_16x16x32_bf16 v[108:111], v[140:143], v[194:197], v[108:111]
	v_mfma_f32_16x16x32_bf16 v[104:107], v[154:157], v[194:197], v[104:107]
	v_mfma_f32_16x16x32_bf16 v[92:95], v[140:143], v[202:205], v[92:95]
	v_mfma_f32_16x16x32_bf16 v[88:91], v[154:157], v[202:205], v[88:91]
	v_mfma_f32_16x16x32_bf16 v[76:79], v[140:143], v[218:221], v[76:79]
	v_mfma_f32_16x16x32_bf16 v[72:75], v[154:157], v[218:221], v[72:75]
	v_mfma_f32_16x16x32_bf16 v[124:127], v[150:153], v[190:193], v[124:127]
	v_mfma_f32_16x16x32_bf16 v[120:123], v[158:161], v[190:193], v[120:123]
	v_mfma_f32_16x16x32_bf16 v[108:111], v[150:153], v[198:201], v[108:111]
	v_mfma_f32_16x16x32_bf16 v[104:107], v[158:161], v[198:201], v[104:107]
	v_mfma_f32_16x16x32_bf16 v[92:95], v[150:153], v[214:217], v[92:95]
	v_mfma_f32_16x16x32_bf16 v[88:91], v[158:161], v[214:217], v[88:91]
	v_mfma_f32_16x16x32_bf16 v[76:79], v[150:153], v[222:225], v[76:79]
	v_mfma_f32_16x16x32_bf16 v[72:75], v[158:161], v[222:225], v[72:75]
	s_setprio 0
	s_setprio 1
	v_mfma_f32_16x16x32_bf16 v[116:119], v[162:165], v[178:181], v[116:119]
	v_mfma_f32_16x16x32_bf16 v[112:115], v[170:173], v[178:181], v[112:115]
	v_mfma_f32_16x16x32_bf16 v[100:103], v[162:165], v[194:197], v[100:103]
	v_mfma_f32_16x16x32_bf16 v[96:99], v[170:173], v[194:197], v[96:99]
	v_mfma_f32_16x16x32_bf16 v[84:87], v[162:165], v[202:205], v[84:87]
	v_mfma_f32_16x16x32_bf16 v[80:83], v[170:173], v[202:205], v[80:83]
	v_mfma_f32_16x16x32_bf16 v[68:71], v[162:165], v[218:221], v[68:71]
	v_mfma_f32_16x16x32_bf16 v[64:67], v[170:173], v[218:221], v[64:67]
	v_mfma_f32_16x16x32_bf16 v[116:119], v[166:169], v[190:193], v[116:119]
	v_mfma_f32_16x16x32_bf16 v[112:115], v[174:177], v[190:193], v[112:115]
	v_mfma_f32_16x16x32_bf16 v[100:103], v[166:169], v[198:201], v[100:103]
	v_mfma_f32_16x16x32_bf16 v[96:99], v[174:177], v[198:201], v[96:99]
	v_mfma_f32_16x16x32_bf16 v[84:87], v[166:169], v[214:217], v[84:87]
	v_mfma_f32_16x16x32_bf16 v[80:83], v[174:177], v[214:217], v[80:83]
	v_mfma_f32_16x16x32_bf16 v[68:71], v[166:169], v[222:225], v[68:71]
	v_mfma_f32_16x16x32_bf16 v[64:67], v[174:177], v[222:225], v[64:67]
	s_setprio 0
	s_barrier
; #define PG8_STAGE(bufoff, gbase, voff) do { _Pragma("unroll") for (int _i = 0; _i < 2; ++_i) \
;         __builtin_amdgcn_global_load_lds((const unsigned*)((const char*)(gbase) + (voff)[_i]), (PG8_LAS unsigned*)(lds + (bufoff) + ldsw + _i * 8192), 16, 0, 0); } while (0)
; #define PG8_LDA(dst, b, h) do { _Pragma("unroll") for (int m = 0; m < 4; ++m) _Pragma("unroll") for (int k = 0; k < 2; ++k) dst[m][k] = *(const PG8_LAS bf16x8*)(lds + PG8_SA(b, h) + aoff + m * 2048 + k * 1024); } while (0)
; #define PG8_MMA(ai, bj, At, Bt) do { __builtin_amdgcn_s_setprio(1); _Pragma("unroll") for (int m = 0; m < 4; ++m) _Pragma("unroll") for (int n = 0; n < 2; ++n) _Pragma("unroll") for (int k = 0; k < 2; ++k) \
;         acc[ai][bj][m][n] = __builtin_amdgcn_mfma_f32_16x16x32_bf16(Bt[n][k], At[m][k], acc[ai][bj][m][n], 0, 0, 0); __builtin_amdgcn_s_setprio(0); } while (0)
; #define PG8_WAIT_V(n) asm volatile("s_waitcnt vmcnt(" #n ")" ::: "memory")
; #define PG8_WAIT_L(n) asm volatile("s_waitcnt lgkmcnt(" #n ")" ::: "memory")
; #define PG8_BAR __builtin_amdgcn_s_barrier()
; #define PG8_SCHED __builtin_amdgcn_sched_barrier(0)
; template <class Epi, class Sched, bool ALIGN_EPI = false, bool SP2 = false>
; __device__ __forceinline__ void gemm_phase(PG8_LAS unsigned char* lds, const Gemm g, const Sched& S, const Epi& E, const int wid_in) {
;     ...
;         for (int t = 0; t < nt; t += 2) {
;             const bool last = (t == nt - 2);
;             const char* a1 = cA + (size_t)(t + 1) * kstep;
;             const char* a2 = last ? nA : cA + (size_t)(t + 2) * kstep; const char* b2 = last ? nB : cB + (size_t)(t + 2) * kstep;
;             const char* a3 = a2 + kstep; const char* b3 = b2 + kstep;
;             if (last && has_next) S.a_ready(nxt);
;     ...
;             PG8_LDA(At, 1, 1); PG8_STAGE(PG8_SB(1, 0), b3, voffB); PG8_STAGE(PG8_SB(1, 1), b3 + hstep, voffB); PG8_STAGE(PG8_SA(1, 0), a3, voffA);
;             PG8_WAIT_V(8); PG8_WAIT_L(0); PG8_BAR; PG8_MMA(1, 0, At, B0); PG8_MMA(1, 1, At, B1); PG8_BAR; PG8_SCHED;
	s_add_i32 s24, s45, s28
	v_lshl_add_u64 v[144:145], v[144:145], 0, s[74:75]
	s_mov_b32 m0, s24
	ds_read_b128 v[178:181], v149 offset:49152
	ds_read_b128 v[190:193], v149 offset:50176
	ds_read_b128 v[194:197], v149 offset:51200
	ds_read_b128 v[198:201], v149 offset:52224
	ds_read_b128 v[202:205], v149 offset:53248
	ds_read_b128 v[214:217], v149 offset:54272
	ds_read_b128 v[218:221], v149 offset:55296
	ds_read_b128 v[222:225], v149 offset:56320
	global_load_lds_dwordx4 v[144:145], off
	s_add_i32 m0, s24, 0x2000
	s_add_u32 s6, s6, 0x80080
	v_lshl_add_u64 v[144:145], v[188:189], 0, s[74:75]
	s_addc_u32 s7, s7, 0
	s_add_i32 s24, s46, s28
	global_load_lds_dwordx4 v[144:145], off
	v_lshl_add_u64 v[144:145], s[6:7], 0, v[182:183]
	s_mov_b32 m0, s24
	s_nop 0
	global_load_lds_dwordx4 v[144:145], off
	v_lshl_add_u64 v[144:145], s[6:7], 0, v[128:129]
	s_add_i32 m0, s24, 0x2000
	s_nop 0
	global_load_lds_dwordx4 v[144:145], off
	v_lshl_add_u64 v[144:145], v[226:227], 0, s[74:75]
	s_mov_b32 m0, s35
	s_nop 0
	global_load_lds_dwordx4 v[144:145], off
	v_lshl_add_u64 v[144:145], v[228:229], 0, s[74:75]
	s_mov_b32 m0, s36
	s_nop 0
	global_load_lds_dwordx4 v[144:145], off
	s_waitcnt vmcnt(8)
	s_waitcnt lgkmcnt(0)
	s_barrier
	s_setprio 1
	s_waitcnt lgkmcnt(0)
	v_mfma_f32_16x16x32_bf16 v[60:63], v[140:143], v[178:181], v[60:63]
	v_mfma_f32_16x16x32_bf16 v[56:59], v[154:157], v[178:181], v[56:59]
	v_mfma_f32_16x16x32_bf16 v[44:47], v[140:143], v[194:197], v[44:47]
	v_mfma_f32_16x16x32_bf16 v[40:43], v[154:157], v[194:197], v[40:43]
	v_mfma_f32_16x16x32_bf16 v[28:31], v[140:143], v[202:205], v[28:31]
	v_mfma_f32_16x16x32_bf16 v[24:27], v[154:157], v[202:205], v[24:27]
	v_mfma_f32_16x16x32_bf16 v[12:15], v[140:143], v[218:221], v[12:15]
	v_mfma_f32_16x16x32_bf16 v[8:11], v[154:157], v[218:221], v[8:11]
	v_mfma_f32_16x16x32_bf16 v[60:63], v[150:153], v[190:193], v[60:63]
	v_mfma_f32_16x16x32_bf16 v[56:59], v[158:161], v[190:193], v[56:59]
	v_mfma_f32_16x16x32_bf16 v[44:47], v[150:153], v[198:201], v[44:47]
	v_mfma_f32_16x16x32_bf16 v[40:43], v[158:161], v[198:201], v[40:43]
	v_mfma_f32_16x16x32_bf16 v[28:31], v[150:153], v[214:217], v[28:31]
	v_mfma_f32_16x16x32_bf16 v[24:27], v[158:161], v[214:217], v[24:27]
	v_mfma_f32_16x16x32_bf16 v[12:15], v[150:153], v[222:225], v[12:15]
	v_mfma_f32_16x16x32_bf16 v[8:11], v[158:161], v[222:225], v[8:11]
	s_setprio 0
	s_setprio 1
	v_mfma_f32_16x16x32_bf16 v[52:55], v[162:165], v[178:181], v[52:55]
	v_mfma_f32_16x16x32_bf16 v[48:51], v[170:173], v[178:181], v[48:51]
	v_mfma_f32_16x16x32_bf16 v[36:39], v[162:165], v[194:197], v[36:39]
	v_mfma_f32_16x16x32_bf16 v[32:35], v[170:173], v[194:197], v[32:35]
	v_mfma_f32_16x16x32_bf16 v[20:23], v[162:165], v[202:205], v[20:23]
	v_mfma_f32_16x16x32_bf16 v[16:19], v[170:173], v[202:205], v[16:19]
	v_mfma_f32_16x16x32_bf16 v[4:7], v[162:165], v[218:221], v[4:7]
	v_mfma_f32_16x16x32_bf16 v[0:3], v[170:173], v[218:221], v[0:3]
	v_mfma_f32_16x16x32_bf16 v[52:55], v[166:169], v[190:193], v[52:55]
	v_mfma_f32_16x16x32_bf16 v[48:51], v[174:177], v[190:193], v[48:51]
	v_mfma_f32_16x16x32_bf16 v[36:39], v[166:169], v[198:201], v[36:39]
	v_mfma_f32_16x16x32_bf16 v[32:35], v[174:177], v[198:201], v[32:35]
	v_mfma_f32_16x16x32_bf16 v[20:23], v[166:169], v[214:217], v[20:23]
	v_mfma_f32_16x16x32_bf16 v[16:19], v[174:177], v[214:217], v[16:19]
	v_mfma_f32_16x16x32_bf16 v[4:7], v[166:169], v[222:225], v[4:7]
	v_mfma_f32_16x16x32_bf16 v[0:3], v[174:177], v[222:225], v[0:3]
	s_setprio 0
	s_add_i32 s44, s44, 2
	s_add_u32 s4, s4, 0x100
	s_addc_u32 s5, s5, 0
	s_add_u32 s42, s42, 0x100
	s_addc_u32 s43, s43, 0
	s_cmp_gt_u32 s44, 29
	s_cbranch_scc1 .Lrot_x_167
	s_add_u32 s6, s4, 0xfff80080
	s_addc_u32 s7, s5, -1
	s_add_i32 s45, 0, 0x10000
	s_cmp_eq_u32 s44, 28
	s_cselect_b32 s25, s19, s7
	s_cselect_b32 s24, s40, s6
	s_cselect_b32 s7, s17, s43
	s_cselect_b32 s6, s41, s42
	s_add_i32 s48, 0, 0x14000
	s_barrier
	s_branch .Lrot_h_167

; #define PG8_STAGE(bufoff, gbase, voff) do { _Pragma("unroll") for (int _i = 0; _i < 2; ++_i) \
;         __builtin_amdgcn_global_load_lds((const unsigned*)((const char*)(gbase) + (voff)[_i]), (PG8_LAS unsigned*)(lds + (bufoff) + ldsw + _i * 8192), 16, 0, 0); } while (0)
; #define PG8_LDA(dst, b, h) do { _Pragma("unroll") for (int m = 0; m < 4; ++m) _Pragma("unroll") for (int k = 0; k < 2; ++k) dst[m][k] = *(const PG8_LAS bf16x8*)(lds + PG8_SA(b, h) + aoff + m * 2048 + k * 1024); } while (0)
; #define PG8_LDB(dst, b, h) do { _Pragma("unroll") for (int n = 0; n < 2; ++n) _Pragma("unroll") for (int k = 0; k < 2; ++k) dst[n][k] = *(const PG8_LAS bf16x8*)(lds + PG8_SB(b, h) + boff + n * 2048 + k * 1024); } while (0)
; #define PG8_MMA(ai, bj, At, Bt) do { __builtin_amdgcn_s_setprio(1); _Pragma("unroll") for (int m = 0; m < 4; ++m) _Pragma("unroll") for (int n = 0; n < 2; ++n) _Pragma("unroll") for (int k = 0; k < 2; ++k) \
;         acc[ai][bj][m][n] = __builtin_amdgcn_mfma_f32_16x16x32_bf16(Bt[n][k], At[m][k], acc[ai][bj][m][n], 0, 0, 0); __builtin_amdgcn_s_setprio(0); } while (0)
; #define PG8_WAIT_V(n) asm volatile("s_waitcnt vmcnt(" #n ")" ::: "memory")
; #define PG8_WAIT_L(n) asm volatile("s_waitcnt lgkmcnt(" #n ")" ::: "memory")
; #define PG8_BAR __builtin_amdgcn_s_barrier()
; template <class Epi, class Sched, bool ALIGN_EPI = false, bool SP2 = false>
; __device__ __forceinline__ void gemm_phase(PG8_LAS unsigned char* lds, const Gemm g, const Sched& S, const Epi& E, const int wid_in) {
;     ...
;         for (int t = 0; t < nt; t += 2) {
;             const bool last = (t == nt - 2);
;             const char* a1 = cA + (size_t)(t + 1) * kstep;
;             const char* a2 = last ? nA : cA + (size_t)(t + 2) * kstep; const char* b2 = last ? nB : cB + (size_t)(t + 2) * kstep;
;             const char* a3 = a2 + kstep; const char* b3 = b2 + kstep;
;             if (last && has_next) S.a_ready(nxt);
;             if constexpr (SP2) {
;             PG8_LDB(B0, 0, 0); PG8_LDB(B1, 0, 1); PG8_SCHED; PG8_LDA(At, 0, 0); PG8_STAGE(PG8_SA(1, 1), a1 + hstep, voffA);
;             PG8_WAIT_V(8); PG8_WAIT_L(0); PG8_BAR; PG8_MMA(0, 0, At, B0); PG8_MMA(0, 1, At, B1); PG8_BAR; PG8_SCHED;
;             PG8_LDA(At, 0, 1); PG8_STAGE(PG8_SB(0, 0), b2, voffB); PG8_STAGE(PG8_SB(0, 1), b2 + hstep, voffB); PG8_STAGE(PG8_SA(0, 0), a2, voffA);
.Lrot_h_1099:
	v_add_u32_e32 v88, s55, v205
	v_add_u32_e32 v156, s56, v205
	ds_read_b128 v[72:75], v88
	ds_read_b128 v[80:83], v88 offset:1024
	ds_read_b128 v[84:87], v88 offset:2048
	ds_read_b128 v[88:91], v88 offset:3072
	ds_read_b128 v[144:147], v156
	ds_read_b128 v[148:151], v156 offset:1024
	ds_read_b128 v[152:155], v156 offset:2048
	ds_read_b128 v[156:159], v156 offset:3072
	v_lshl_add_u64 v[180:181], s[4:5], 0, v[192:193]
	s_add_i32 m0, s41, 0xc000
	ds_read_b128 v[160:163], v217
	ds_read_b128 v[164:167], v217 offset:1024
	ds_read_b128 v[168:171], v217 offset:2048
	ds_read_b128 v[172:175], v217 offset:3072
	ds_read_b128 v[176:179], v217 offset:4096
	ds_read_b128 v[196:199], v217 offset:5120
	ds_read_b128 v[200:203], v217 offset:6144
	ds_read_b128 v[218:221], v217 offset:7168
	global_load_lds_dwordx4 v[180:181], off
	v_lshl_add_u64 v[180:181], s[4:5], 0, v[194:195]
	s_add_i32 m0, s41, 0xe000
	s_nop 0
	global_load_lds_dwordx4 v[180:181], off
	s_waitcnt vmcnt(8)
	s_waitcnt lgkmcnt(0)
	s_barrier
	s_setprio 1
	s_waitcnt lgkmcnt(0)
	v_mfma_f32_16x16x32_bf16 v[140:143], v[72:75], v[160:163], v[140:143]
	v_mfma_f32_16x16x32_bf16 v[136:139], v[84:87], v[160:163], v[136:139]
	v_mfma_f32_16x16x32_bf16 v[128:131], v[72:75], v[168:171], v[128:131]
	v_mfma_f32_16x16x32_bf16 v[120:123], v[84:87], v[168:171], v[120:123]
	v_mfma_f32_16x16x32_bf16 v[112:115], v[72:75], v[176:179], v[112:115]
	v_mfma_f32_16x16x32_bf16 v[104:107], v[84:87], v[176:179], v[104:107]
	v_mfma_f32_16x16x32_bf16 v[96:99], v[72:75], v[200:203], v[96:99]
	v_mfma_f32_16x16x32_bf16 v[76:79], v[84:87], v[200:203], v[76:79]
	v_mfma_f32_16x16x32_bf16 v[140:143], v[80:83], v[164:167], v[140:143]
	v_mfma_f32_16x16x32_bf16 v[136:139], v[88:91], v[164:167], v[136:139]
	v_mfma_f32_16x16x32_bf16 v[128:131], v[80:83], v[172:175], v[128:131]
	v_mfma_f32_16x16x32_bf16 v[120:123], v[88:91], v[172:175], v[120:123]
	v_mfma_f32_16x16x32_bf16 v[112:115], v[80:83], v[196:199], v[112:115]
	v_mfma_f32_16x16x32_bf16 v[104:107], v[88:91], v[196:199], v[104:107]
	v_mfma_f32_16x16x32_bf16 v[96:99], v[80:83], v[218:221], v[96:99]
	v_mfma_f32_16x16x32_bf16 v[76:79], v[88:91], v[218:221], v[76:79]
	s_setprio 0
	s_setprio 1
	v_mfma_f32_16x16x32_bf16 v[132:135], v[144:147], v[160:163], v[132:135]
	v_mfma_f32_16x16x32_bf16 v[124:127], v[152:155], v[160:163], v[124:127]
	v_mfma_f32_16x16x32_bf16 v[116:119], v[144:147], v[168:171], v[116:119]
	v_mfma_f32_16x16x32_bf16 v[108:111], v[152:155], v[168:171], v[108:111]
	v_mfma_f32_16x16x32_bf16 v[100:103], v[144:147], v[176:179], v[100:103]
	v_mfma_f32_16x16x32_bf16 v[92:95], v[152:155], v[176:179], v[92:95]
	v_mfma_f32_16x16x32_bf16 v[68:71], v[144:147], v[200:203], v[68:71]
	v_mfma_f32_16x16x32_bf16 v[64:67], v[152:155], v[200:203], v[64:67]
	v_mfma_f32_16x16x32_bf16 v[132:135], v[148:151], v[164:167], v[132:135]
	v_mfma_f32_16x16x32_bf16 v[124:127], v[156:159], v[164:167], v[124:127]
	v_mfma_f32_16x16x32_bf16 v[116:119], v[148:151], v[172:175], v[116:119]
	v_mfma_f32_16x16x32_bf16 v[108:111], v[156:159], v[172:175], v[108:111]
	v_mfma_f32_16x16x32_bf16 v[100:103], v[148:151], v[196:199], v[100:103]
	v_mfma_f32_16x16x32_bf16 v[92:95], v[156:159], v[196:199], v[92:95]
	v_mfma_f32_16x16x32_bf16 v[68:71], v[148:151], v[218:221], v[68:71]
	v_mfma_f32_16x16x32_bf16 v[64:67], v[156:159], v[218:221], v[64:67]
	s_setprio 0
	s_barrier
	s_add_i32 s4, s55, s40
	v_lshl_add_u64 v[180:181], s[26:27], 0, v[182:183]
	s_mov_b32 m0, s4
	ds_read_b128 v[160:163], v217 offset:16384
	ds_read_b128 v[164:167], v217 offset:17408
	ds_read_b128 v[168:171], v217 offset:18432
	ds_read_b128 v[172:175], v217 offset:19456
	ds_read_b128 v[176:179], v217 offset:20480
	ds_read_b128 v[196:199], v217 offset:21504
	ds_read_b128 v[200:203], v217 offset:22528
	ds_read_b128 v[218:221], v217 offset:23552
	global_load_lds_dwordx4 v[180:181], off
	s_add_i32 m0, s4, 0x2000
	s_add_u32 s4, s26, 0x80000
	v_lshl_add_u64 v[188:189], s[26:27], 0, v[190:191]
	s_addc_u32 s5, s27, 0
	s_add_i32 s55, s56, s40
	global_load_lds_dwordx4 v[188:189], off
	v_lshl_add_u64 v[222:223], s[4:5], 0, v[182:183]
	s_mov_b32 m0, s55
	v_lshl_add_u64 v[224:225], s[28:29], 0, v[190:191]
	global_load_lds_dwordx4 v[222:223], off
	v_lshl_add_u64 v[222:223], s[4:5], 0, v[190:191]
	s_add_i32 m0, s55, 0x2000
	s_nop 0
	global_load_lds_dwordx4 v[222:223], off
	v_lshl_add_u64 v[222:223], s[28:29], 0, v[182:183]
	s_mov_b32 m0, s41
	s_nop 0
	global_load_lds_dwordx4 v[222:223], off
	s_mov_b32 m0, s42
	s_nop 0
	global_load_lds_dwordx4 v[224:225], off
	s_waitcnt vmcnt(8)
	s_waitcnt lgkmcnt(0)
	s_barrier
; #define PG8_STAGE(bufoff, gbase, voff) do { _Pragma("unroll") for (int _i = 0; _i < 2; ++_i) \
;         __builtin_amdgcn_global_load_lds((const unsigned*)((const char*)(gbase) + (voff)[_i]), (PG8_LAS unsigned*)(lds + (bufoff) + ldsw + _i * 8192), 16, 0, 0); } while (0)
; #define PG8_LDA(dst, b, h) do { _Pragma("unroll") for (int m = 0; m < 4; ++m) _Pragma("unroll") for (int k = 0; k < 2; ++k) dst[m][k] = *(const PG8_LAS bf16x8*)(lds + PG8_SA(b, h) + aoff + m * 2048 + k * 1024); } while (0)
; #define PG8_LDB(dst, b, h) do { _Pragma("unroll") for (int n = 0; n < 2; ++n) _Pragma("unroll") for (int k = 0; k < 2; ++k) dst[n][k] = *(const PG8_LAS bf16x8*)(lds + PG8_SB(b, h) + boff + n * 2048 + k * 1024); } while (0)
; #define PG8_MMA(ai, bj, At, Bt) do { __builtin_amdgcn_s_setprio(1); _Pragma("unroll") for (int m = 0; m < 4; ++m) _Pragma("unroll") for (int n = 0; n < 2; ++n) _Pragma("unroll") for (int k = 0; k < 2; ++k) \
;         acc[ai][bj][m][n] = __builtin_amdgcn_mfma_f32_16x16x32_bf16(Bt[n][k], At[m][k], acc[ai][bj][m][n], 0, 0, 0); __builtin_amdgcn_s_setprio(0); } while (0)
; #define PG8_WAIT_V(n) asm volatile("s_waitcnt vmcnt(" #n ")" ::: "memory")
; #define PG8_WAIT_L(n) asm volatile("s_waitcnt lgkmcnt(" #n ")" ::: "memory")
; #define PG8_BAR __builtin_amdgcn_s_barrier()
; #define PG8_SCHED __builtin_amdgcn_sched_barrier(0)
; template <class Epi, class Sched, bool ALIGN_EPI = false, bool SP2 = false>
; __device__ __forceinline__ void gemm_phase(PG8_LAS unsigned char* lds, const Gemm g, const Sched& S, const Epi& E, const int wid_in) {
;     ...
;             PG8_WAIT_V(8); PG8_WAIT_L(0); PG8_BAR; PG8_MMA(1, 0, At, B0); PG8_MMA(1, 1, At, B1); PG8_BAR; PG8_SCHED;
;             PG8_LDB(B0, 1, 0); PG8_LDB(B1, 1, 1); PG8_SCHED; PG8_LDA(At, 1, 0); PG8_STAGE(PG8_SA(0, 1), a2 + hstep, voffA);
;             PG8_WAIT_V(8); PG8_WAIT_L(0); PG8_BAR; PG8_MMA(0, 0, At, B0); PG8_MMA(0, 1, At, B1); PG8_BAR; PG8_SCHED;
	s_setprio 1
	s_waitcnt lgkmcnt(0)
	v_mfma_f32_16x16x32_bf16 v[60:63], v[72:75], v[160:163], v[60:63]
	v_mfma_f32_16x16x32_bf16 v[56:59], v[84:87], v[160:163], v[56:59]
	v_mfma_f32_16x16x32_bf16 v[48:51], v[72:75], v[168:171], v[48:51]
	v_mfma_f32_16x16x32_bf16 v[40:43], v[84:87], v[168:171], v[40:43]
	v_mfma_f32_16x16x32_bf16 v[32:35], v[72:75], v[176:179], v[32:35]
	v_mfma_f32_16x16x32_bf16 v[24:27], v[84:87], v[176:179], v[24:27]
	v_mfma_f32_16x16x32_bf16 v[16:19], v[72:75], v[200:203], v[16:19]
	v_mfma_f32_16x16x32_bf16 v[8:11], v[84:87], v[200:203], v[8:11]
	v_mfma_f32_16x16x32_bf16 v[60:63], v[80:83], v[164:167], v[60:63]
	v_mfma_f32_16x16x32_bf16 v[56:59], v[88:91], v[164:167], v[56:59]
	v_mfma_f32_16x16x32_bf16 v[48:51], v[80:83], v[172:175], v[48:51]
	v_mfma_f32_16x16x32_bf16 v[40:43], v[88:91], v[172:175], v[40:43]
	v_mfma_f32_16x16x32_bf16 v[32:35], v[80:83], v[196:199], v[32:35]
	v_mfma_f32_16x16x32_bf16 v[24:27], v[88:91], v[196:199], v[24:27]
	v_mfma_f32_16x16x32_bf16 v[16:19], v[80:83], v[218:221], v[16:19]
	v_mfma_f32_16x16x32_bf16 v[8:11], v[88:91], v[218:221], v[8:11]
	s_setprio 0
	s_setprio 1
	v_mfma_f32_16x16x32_bf16 v[52:55], v[144:147], v[160:163], v[52:55]
	v_mfma_f32_16x16x32_bf16 v[44:47], v[152:155], v[160:163], v[44:47]
	v_mfma_f32_16x16x32_bf16 v[36:39], v[144:147], v[168:171], v[36:39]
	v_mfma_f32_16x16x32_bf16 v[28:31], v[152:155], v[168:171], v[28:31]
	v_mfma_f32_16x16x32_bf16 v[20:23], v[144:147], v[176:179], v[20:23]
	v_mfma_f32_16x16x32_bf16 v[12:15], v[152:155], v[176:179], v[12:15]
	v_mfma_f32_16x16x32_bf16 v[4:7], v[144:147], v[200:203], v[4:7]
	v_mfma_f32_16x16x32_bf16 v[0:3], v[152:155], v[200:203], v[0:3]
	v_mfma_f32_16x16x32_bf16 v[52:55], v[148:151], v[164:167], v[52:55]
	v_mfma_f32_16x16x32_bf16 v[44:47], v[156:159], v[164:167], v[44:47]
	v_mfma_f32_16x16x32_bf16 v[36:39], v[148:151], v[172:175], v[36:39]
	v_mfma_f32_16x16x32_bf16 v[28:31], v[156:159], v[172:175], v[28:31]
	v_mfma_f32_16x16x32_bf16 v[20:23], v[148:151], v[196:199], v[20:23]
	v_mfma_f32_16x16x32_bf16 v[12:15], v[156:159], v[196:199], v[12:15]
	v_mfma_f32_16x16x32_bf16 v[4:7], v[148:151], v[218:221], v[4:7]
	v_mfma_f32_16x16x32_bf16 v[0:3], v[156:159], v[218:221], v[0:3]
	s_setprio 0
	s_barrier
	s_add_i32 s55, 0, 0x18000
	s_add_i32 s56, 0, 0x1c000
	v_add_u32_e32 v88, s55, v205
	v_add_u32_e32 v156, s56, v205
	ds_read_b128 v[72:75], v88
	ds_read_b128 v[80:83], v88 offset:1024
	ds_read_b128 v[84:87], v88 offset:2048
	ds_read_b128 v[88:91], v88 offset:3072
	ds_read_b128 v[144:147], v156
	ds_read_b128 v[148:151], v156 offset:1024
	ds_read_b128 v[152:155], v156 offset:2048
	ds_read_b128 v[156:159], v156 offset:3072
	s_add_u32 s4, s28, 0x80000
	s_addc_u32 s5, s29, 0
	s_mov_b32 m0, s43
	v_lshl_add_u64 v[226:227], s[4:5], 0, v[182:183]
	ds_read_b128 v[160:163], v217 offset:32768
	ds_read_b128 v[164:167], v217 offset:33792
	ds_read_b128 v[168:171], v217 offset:34816
	ds_read_b128 v[172:175], v217 offset:35840
	ds_read_b128 v[176:179], v217 offset:36864
	ds_read_b128 v[196:199], v217 offset:37888
	ds_read_b128 v[200:203], v217 offset:38912
	ds_read_b128 v[218:221], v217 offset:39936
	global_load_lds_dwordx4 v[226:227], off
	v_lshl_add_u64 v[226:227], s[4:5], 0, v[190:191]
	s_mov_b32 m0, s44
	s_nop 0
	global_load_lds_dwordx4 v[226:227], off
	s_waitcnt vmcnt(8)
	s_waitcnt lgkmcnt(0)
	s_barrier
	s_setprio 1
	s_waitcnt lgkmcnt(0)
	v_mfma_f32_16x16x32_bf16 v[140:143], v[72:75], v[160:163], v[140:143]
	v_mfma_f32_16x16x32_bf16 v[136:139], v[84:87], v[160:163], v[136:139]
	v_mfma_f32_16x16x32_bf16 v[128:131], v[72:75], v[168:171], v[128:131]
	v_mfma_f32_16x16x32_bf16 v[120:123], v[84:87], v[168:171], v[120:123]
	v_mfma_f32_16x16x32_bf16 v[112:115], v[72:75], v[176:179], v[112:115]
	v_mfma_f32_16x16x32_bf16 v[104:107], v[84:87], v[176:179], v[104:107]
	v_mfma_f32_16x16x32_bf16 v[96:99], v[72:75], v[200:203], v[96:99]
	v_mfma_f32_16x16x32_bf16 v[76:79], v[84:87], v[200:203], v[76:79]
	v_mfma_f32_16x16x32_bf16 v[140:143], v[80:83], v[164:167], v[140:143]
	v_mfma_f32_16x16x32_bf16 v[136:139], v[88:91], v[164:167], v[136:139]
	v_mfma_f32_16x16x32_bf16 v[128:131], v[80:83], v[172:175], v[128:131]
	v_mfma_f32_16x16x32_bf16 v[120:123], v[88:91], v[172:175], v[120:123]
	v_mfma_f32_16x16x32_bf16 v[112:115], v[80:83], v[196:199], v[112:115]
	v_mfma_f32_16x16x32_bf16 v[104:107], v[88:91], v[196:199], v[104:107]
	v_mfma_f32_16x16x32_bf16 v[96:99], v[80:83], v[218:221], v[96:99]
	v_mfma_f32_16x16x32_bf16 v[76:79], v[88:91], v[218:221], v[76:79]
	s_setprio 0
	s_setprio 1
	v_mfma_f32_16x16x32_bf16 v[132:135], v[144:147], v[160:163], v[132:135]
	v_mfma_f32_16x16x32_bf16 v[124:127], v[152:155], v[160:163], v[124:127]
	v_mfma_f32_16x16x32_bf16 v[116:119], v[144:147], v[168:171], v[116:119]
	v_mfma_f32_16x16x32_bf16 v[108:111], v[152:155], v[168:171], v[108:111]
	v_mfma_f32_16x16x32_bf16 v[100:103], v[144:147], v[176:179], v[100:103]
	v_mfma_f32_16x16x32_bf16 v[92:95], v[152:155], v[176:179], v[92:95]
	v_mfma_f32_16x16x32_bf16 v[68:71], v[144:147], v[200:203], v[68:71]
	v_mfma_f32_16x16x32_bf16 v[64:67], v[152:155], v[200:203], v[64:67]
	v_mfma_f32_16x16x32_bf16 v[132:135], v[148:151], v[164:167], v[132:135]
	v_mfma_f32_16x16x32_bf16 v[124:127], v[156:159], v[164:167], v[124:127]
	v_mfma_f32_16x16x32_bf16 v[116:119], v[148:151], v[172:175], v[116:119]
	v_mfma_f32_16x16x32_bf16 v[108:111], v[156:159], v[172:175], v[108:111]
	v_mfma_f32_16x16x32_bf16 v[100:103], v[148:151], v[196:199], v[100:103]
	v_mfma_f32_16x16x32_bf16 v[92:95], v[156:159], v[196:199], v[92:95]
	v_mfma_f32_16x16x32_bf16 v[68:71], v[148:151], v[218:221], v[68:71]
	v_mfma_f32_16x16x32_bf16 v[64:67], v[156:159], v[218:221], v[64:67]
	s_setprio 0
	s_barrier
; #define PG8_STAGE(bufoff, gbase, voff) do { _Pragma("unroll") for (int _i = 0; _i < 2; ++_i) \
;         __builtin_amdgcn_global_load_lds((const unsigned*)((const char*)(gbase) + (voff)[_i]), (PG8_LAS unsigned*)(lds + (bufoff) + ldsw + _i * 8192), 16, 0, 0); } while (0)
; #define PG8_LDA(dst, b, h) do { _Pragma("unroll") for (int m = 0; m < 4; ++m) _Pragma("unroll") for (int k = 0; k < 2; ++k) dst[m][k] = *(const PG8_LAS bf16x8*)(lds + PG8_SA(b, h) + aoff + m * 2048 + k * 1024); } while (0)
; #define PG8_MMA(ai, bj, At, Bt) do { __builtin_amdgcn_s_setprio(1); _Pragma("unroll") for (int m = 0; m < 4; ++m) _Pragma("unroll") for (int n = 0; n < 2; ++n) _Pragma("unroll") for (int k = 0; k < 2; ++k) \
;         acc[ai][bj][m][n] = __builtin_amdgcn_mfma_f32_16x16x32_bf16(Bt[n][k], At[m][k], acc[ai][bj][m][n], 0, 0, 0); __builtin_amdgcn_s_setprio(0); } while (0)
; #define PG8_WAIT_V(n) asm volatile("s_waitcnt vmcnt(" #n ")" ::: "memory")
; #define PG8_WAIT_L(n) asm volatile("s_waitcnt lgkmcnt(" #n ")" ::: "memory")
; #define PG8_BAR __builtin_amdgcn_s_barrier()
; #define PG8_SCHED __builtin_amdgcn_sched_barrier(0)
; template <class Epi, class Sched, bool ALIGN_EPI = false, bool SP2 = false>
; __device__ __forceinline__ void gemm_phase(PG8_LAS unsigned char* lds, const Gemm g, const Sched& S, const Epi& E, const int wid_in) {
;     ...
;         for (int t = 0; t < nt; t += 2) {
;             const bool last = (t == nt - 2);
;             const char* a1 = cA + (size_t)(t + 1) * kstep;
;             const char* a2 = last ? nA : cA + (size_t)(t + 2) * kstep; const char* b2 = last ? nB : cB + (size_t)(t + 2) * kstep;
;             const char* a3 = a2 + kstep; const char* b3 = b2 + kstep;
;             if (last && has_next) S.a_ready(nxt);
;     ...
;             PG8_LDA(At, 1, 1); PG8_STAGE(PG8_SB(1, 0), b3, voffB); PG8_STAGE(PG8_SB(1, 1), b3 + hstep, voffB); PG8_STAGE(PG8_SA(1, 0), a3, voffA);
;             PG8_WAIT_V(8); PG8_WAIT_L(0); PG8_BAR; PG8_MMA(1, 0, At, B0); PG8_MMA(1, 1, At, B1); PG8_BAR; PG8_SCHED;
	s_add_i32 s4, s55, s40
	v_lshl_add_u64 v[180:181], v[180:181], 0, s[74:75]
	s_mov_b32 m0, s4
	ds_read_b128 v[160:163], v217 offset:49152
	ds_read_b128 v[164:167], v217 offset:50176
	ds_read_b128 v[168:171], v217 offset:51200
	ds_read_b128 v[172:175], v217 offset:52224
	ds_read_b128 v[176:179], v217 offset:53248
	ds_read_b128 v[196:199], v217 offset:54272
	ds_read_b128 v[200:203], v217 offset:55296
	ds_read_b128 v[218:221], v217 offset:56320
	global_load_lds_dwordx4 v[180:181], off
	s_add_i32 m0, s4, 0x2000
	s_add_u32 s4, s26, 0x80080
	v_lshl_add_u64 v[180:181], v[188:189], 0, s[74:75]
	s_addc_u32 s5, s27, 0
	s_add_i32 s26, s56, s40
	global_load_lds_dwordx4 v[180:181], off
	v_lshl_add_u64 v[180:181], s[4:5], 0, v[182:183]
	s_mov_b32 m0, s26
	s_nop 0
	global_load_lds_dwordx4 v[180:181], off
	v_lshl_add_u64 v[180:181], s[4:5], 0, v[190:191]
	s_add_i32 m0, s26, 0x2000
	s_nop 0
	global_load_lds_dwordx4 v[180:181], off
	v_lshl_add_u64 v[180:181], v[222:223], 0, s[74:75]
	s_mov_b32 m0, s45
	s_nop 0
	global_load_lds_dwordx4 v[180:181], off
	v_lshl_add_u64 v[180:181], v[224:225], 0, s[74:75]
	s_mov_b32 m0, s46
	s_nop 0
	global_load_lds_dwordx4 v[180:181], off
	s_waitcnt vmcnt(8)
	s_waitcnt lgkmcnt(0)
	s_barrier
	s_setprio 1
	s_waitcnt lgkmcnt(0)
	v_mfma_f32_16x16x32_bf16 v[60:63], v[72:75], v[160:163], v[60:63]
	v_mfma_f32_16x16x32_bf16 v[56:59], v[84:87], v[160:163], v[56:59]
	v_mfma_f32_16x16x32_bf16 v[48:51], v[72:75], v[168:171], v[48:51]
	v_mfma_f32_16x16x32_bf16 v[40:43], v[84:87], v[168:171], v[40:43]
	v_mfma_f32_16x16x32_bf16 v[32:35], v[72:75], v[176:179], v[32:35]
	v_mfma_f32_16x16x32_bf16 v[24:27], v[84:87], v[176:179], v[24:27]
	v_mfma_f32_16x16x32_bf16 v[16:19], v[72:75], v[200:203], v[16:19]
	v_mfma_f32_16x16x32_bf16 v[8:11], v[84:87], v[200:203], v[8:11]
	v_mfma_f32_16x16x32_bf16 v[60:63], v[80:83], v[164:167], v[60:63]
	v_mfma_f32_16x16x32_bf16 v[56:59], v[88:91], v[164:167], v[56:59]
	v_mfma_f32_16x16x32_bf16 v[48:51], v[80:83], v[172:175], v[48:51]
	v_mfma_f32_16x16x32_bf16 v[40:43], v[88:91], v[172:175], v[40:43]
	v_mfma_f32_16x16x32_bf16 v[32:35], v[80:83], v[196:199], v[32:35]
	v_mfma_f32_16x16x32_bf16 v[24:27], v[88:91], v[196:199], v[24:27]
	v_mfma_f32_16x16x32_bf16 v[16:19], v[80:83], v[218:221], v[16:19]
	v_mfma_f32_16x16x32_bf16 v[8:11], v[88:91], v[218:221], v[8:11]
	s_setprio 0
	s_setprio 1
	v_mfma_f32_16x16x32_bf16 v[52:55], v[144:147], v[160:163], v[52:55]
	v_mfma_f32_16x16x32_bf16 v[44:47], v[152:155], v[160:163], v[44:47]
	v_mfma_f32_16x16x32_bf16 v[36:39], v[144:147], v[168:171], v[36:39]
	v_mfma_f32_16x16x32_bf16 v[28:31], v[152:155], v[168:171], v[28:31]
	v_mfma_f32_16x16x32_bf16 v[20:23], v[144:147], v[176:179], v[20:23]
	v_mfma_f32_16x16x32_bf16 v[12:15], v[152:155], v[176:179], v[12:15]
	v_mfma_f32_16x16x32_bf16 v[4:7], v[144:147], v[200:203], v[4:7]
	v_mfma_f32_16x16x32_bf16 v[0:3], v[152:155], v[200:203], v[0:3]
	v_mfma_f32_16x16x32_bf16 v[52:55], v[148:151], v[164:167], v[52:55]
	v_mfma_f32_16x16x32_bf16 v[44:47], v[156:159], v[164:167], v[44:47]
	v_mfma_f32_16x16x32_bf16 v[36:39], v[148:151], v[172:175], v[36:39]
	v_mfma_f32_16x16x32_bf16 v[28:31], v[156:159], v[172:175], v[28:31]
	v_mfma_f32_16x16x32_bf16 v[20:23], v[148:151], v[196:199], v[20:23]
	v_mfma_f32_16x16x32_bf16 v[12:15], v[156:159], v[196:199], v[12:15]
	v_mfma_f32_16x16x32_bf16 v[4:7], v[148:151], v[218:221], v[4:7]
	v_mfma_f32_16x16x32_bf16 v[0:3], v[156:159], v[218:221], v[0:3]
	s_setprio 0
	s_add_i32 s54, s54, 2
	s_add_u32 s52, s52, 0x100
	s_addc_u32 s53, s53, 0
	s_cmp_gt_u32 s54, 29
	s_mov_b64 s[4:5], s[24:25]
	s_cbranch_scc1 .Lrot_x_1099
	s_add_u32 s24, s4, 0x100
	s_addc_u32 s25, s5, 0
	s_add_i32 s55, 0, 0x10000
	s_cmp_eq_u32 s54, 28
	s_cselect_b32 s29, s19, s25
	s_cselect_b32 s28, s50, s24
	s_cselect_b32 s27, s17, s53
	s_cselect_b32 s26, s51, s52
	s_add_i32 s56, 0, 0x14000
	s_barrier
	s_branch .Lrot_h_1099

; #define PG8_STAGE(bufoff, gbase, voff) do { _Pragma("unroll") for (int _i = 0; _i < 2; ++_i) \
;         __builtin_amdgcn_global_load_lds((const unsigned*)((const char*)(gbase) + (voff)[_i]), (PG8_LAS unsigned*)(lds + (bufoff) + ldsw + _i * 8192), 16, 0, 0); } while (0)
; #define PG8_LDA(dst, b, h) do { _Pragma("unroll") for (int m = 0; m < 4; ++m) _Pragma("unroll") for (int k = 0; k < 2; ++k) dst[m][k] = *(const PG8_LAS bf16x8*)(lds + PG8_SA(b, h) + aoff + m * 2048 + k * 1024); } while (0)
; #define PG8_LDB(dst, b, h) do { _Pragma("unroll") for (int n = 0; n < 2; ++n) _Pragma("unroll") for (int k = 0; k < 2; ++k) dst[n][k] = *(const PG8_LAS bf16x8*)(lds + PG8_SB(b, h) + boff + n * 2048 + k * 1024); } while (0)
; #define PG8_MMA(ai, bj, At, Bt) do { __builtin_amdgcn_s_setprio(1); _Pragma("unroll") for (int m = 0; m < 4; ++m) _Pragma("unroll") for (int n = 0; n < 2; ++n) _Pragma("unroll") for (int k = 0; k < 2; ++k) \
;         acc[ai][bj][m][n] = __builtin_amdgcn_mfma_f32_16x16x32_bf16(Bt[n][k], At[m][k], acc[ai][bj][m][n], 0, 0, 0); __builtin_amdgcn_s_setprio(0); } while (0)
; #define PG8_WAIT_V(n) asm volatile("s_waitcnt vmcnt(" #n ")" ::: "memory")
; #define PG8_WAIT_L(n) asm volatile("s_waitcnt lgkmcnt(" #n ")" ::: "memory")
; #define PG8_BAR __builtin_amdgcn_s_barrier()
; template <class Epi, class Sched, bool ALIGN_EPI = false, bool SP2 = false>
; __device__ __forceinline__ void gemm_phase(PG8_LAS unsigned char* lds, const Gemm g, const Sched& S, const Epi& E, const int wid_in) {
;     ...
;         for (int t = 0; t < nt; t += 2) {
;             const bool last = (t == nt - 2);
;             const char* a1 = cA + (size_t)(t + 1) * kstep;
;             const char* a2 = last ? nA : cA + (size_t)(t + 2) * kstep; const char* b2 = last ? nB : cB + (size_t)(t + 2) * kstep;
;             const char* a3 = a2 + kstep; const char* b3 = b2 + kstep;
;             if (last && has_next) S.a_ready(nxt);
;             if constexpr (SP2) {
;             PG8_LDB(B0, 0, 0); PG8_LDB(B1, 0, 1); PG8_SCHED; PG8_LDA(At, 0, 0); PG8_STAGE(PG8_SA(1, 1), a1 + hstep, voffA);
;             PG8_WAIT_V(8); PG8_WAIT_L(0); PG8_BAR; PG8_MMA(0, 0, At, B0); PG8_MMA(0, 1, At, B1); PG8_BAR; PG8_SCHED;
;             PG8_LDA(At, 0, 1); PG8_STAGE(PG8_SB(0, 0), b2, voffB); PG8_STAGE(PG8_SB(0, 1), b2 + hstep, voffB); PG8_STAGE(PG8_SA(0, 0), a2, voffA);
.Lrot_h_1212:
	v_add_u32_e32 v154, s48, v147
	v_add_u32_e32 v170, s50, v147
	ds_read_b128 v[138:141], v154
	ds_read_b128 v[142:145], v154 offset:1024
	ds_read_b128 v[150:153], v154 offset:2048
	ds_read_b128 v[154:157], v154 offset:3072
	ds_read_b128 v[158:161], v170
	ds_read_b128 v[162:165], v170 offset:1024
	ds_read_b128 v[166:169], v170 offset:2048
	ds_read_b128 v[170:173], v170 offset:3072
	v_lshl_add_u64 v[204:205], s[4:5], 0, v[134:135]
	s_add_i32 m0, s26, 0xc000
	ds_read_b128 v[174:177], v149
	ds_read_b128 v[178:181], v149 offset:1024
	ds_read_b128 v[188:191], v149 offset:2048
	ds_read_b128 v[192:195], v149 offset:3072
	ds_read_b128 v[196:199], v149 offset:4096
	ds_read_b128 v[200:203], v149 offset:5120
	ds_read_b128 v[214:217], v149 offset:6144
	ds_read_b128 v[218:221], v149 offset:7168
	global_load_lds_dwordx4 v[204:205], off
	v_lshl_add_u64 v[204:205], s[4:5], 0, v[136:137]
	s_add_i32 m0, s26, 0xe000
	s_nop 0
	global_load_lds_dwordx4 v[204:205], off
	s_waitcnt vmcnt(8)
	s_waitcnt lgkmcnt(0)
	s_barrier
	s_setprio 1
	s_waitcnt lgkmcnt(0)
	v_mfma_f32_16x16x32_bf16 v[124:127], v[138:141], v[174:177], v[124:127]
	v_mfma_f32_16x16x32_bf16 v[120:123], v[150:153], v[174:177], v[120:123]
	v_mfma_f32_16x16x32_bf16 v[108:111], v[138:141], v[188:191], v[108:111]
	v_mfma_f32_16x16x32_bf16 v[104:107], v[150:153], v[188:191], v[104:107]
	v_mfma_f32_16x16x32_bf16 v[92:95], v[138:141], v[196:199], v[92:95]
	v_mfma_f32_16x16x32_bf16 v[88:91], v[150:153], v[196:199], v[88:91]
	v_mfma_f32_16x16x32_bf16 v[76:79], v[138:141], v[214:217], v[76:79]
	v_mfma_f32_16x16x32_bf16 v[72:75], v[150:153], v[214:217], v[72:75]
	v_mfma_f32_16x16x32_bf16 v[124:127], v[142:145], v[178:181], v[124:127]
	v_mfma_f32_16x16x32_bf16 v[120:123], v[154:157], v[178:181], v[120:123]
	v_mfma_f32_16x16x32_bf16 v[108:111], v[142:145], v[192:195], v[108:111]
	v_mfma_f32_16x16x32_bf16 v[104:107], v[154:157], v[192:195], v[104:107]
	v_mfma_f32_16x16x32_bf16 v[92:95], v[142:145], v[200:203], v[92:95]
	v_mfma_f32_16x16x32_bf16 v[88:91], v[154:157], v[200:203], v[88:91]
	v_mfma_f32_16x16x32_bf16 v[76:79], v[142:145], v[218:221], v[76:79]
	v_mfma_f32_16x16x32_bf16 v[72:75], v[154:157], v[218:221], v[72:75]
	s_setprio 0
	s_setprio 1
	v_mfma_f32_16x16x32_bf16 v[116:119], v[158:161], v[174:177], v[116:119]
	v_mfma_f32_16x16x32_bf16 v[112:115], v[166:169], v[174:177], v[112:115]
	v_mfma_f32_16x16x32_bf16 v[100:103], v[158:161], v[188:191], v[100:103]
	v_mfma_f32_16x16x32_bf16 v[96:99], v[166:169], v[188:191], v[96:99]
	v_mfma_f32_16x16x32_bf16 v[84:87], v[158:161], v[196:199], v[84:87]
	v_mfma_f32_16x16x32_bf16 v[80:83], v[166:169], v[196:199], v[80:83]
	v_mfma_f32_16x16x32_bf16 v[68:71], v[158:161], v[214:217], v[68:71]
	v_mfma_f32_16x16x32_bf16 v[64:67], v[166:169], v[214:217], v[64:67]
	v_mfma_f32_16x16x32_bf16 v[116:119], v[162:165], v[178:181], v[116:119]
	v_mfma_f32_16x16x32_bf16 v[112:115], v[170:173], v[178:181], v[112:115]
	v_mfma_f32_16x16x32_bf16 v[100:103], v[162:165], v[192:195], v[100:103]
	v_mfma_f32_16x16x32_bf16 v[96:99], v[170:173], v[192:195], v[96:99]
	v_mfma_f32_16x16x32_bf16 v[84:87], v[162:165], v[200:203], v[84:87]
	v_mfma_f32_16x16x32_bf16 v[80:83], v[170:173], v[200:203], v[80:83]
	v_mfma_f32_16x16x32_bf16 v[68:71], v[162:165], v[218:221], v[68:71]
	v_mfma_f32_16x16x32_bf16 v[64:67], v[170:173], v[218:221], v[64:67]
	s_setprio 0
	s_barrier
	s_add_i32 s48, s48, s25
	v_lshl_add_u64 v[204:205], s[18:19], 0, v[182:183]
	s_mov_b32 m0, s48
	ds_read_b128 v[174:177], v149 offset:16384
	ds_read_b128 v[178:181], v149 offset:17408
	ds_read_b128 v[188:191], v149 offset:18432
	ds_read_b128 v[192:195], v149 offset:19456
	ds_read_b128 v[196:199], v149 offset:20480
	ds_read_b128 v[200:203], v149 offset:21504
	ds_read_b128 v[214:217], v149 offset:22528
	ds_read_b128 v[218:221], v149 offset:23552
	global_load_lds_dwordx4 v[204:205], off
	s_add_i32 m0, s48, 0x2000
	s_add_u32 s48, s18, 0x80000
	v_lshl_add_u64 v[222:223], s[18:19], 0, v[128:129]
	s_addc_u32 s49, s19, 0
	s_add_i32 s50, s50, s25
	global_load_lds_dwordx4 v[222:223], off
	v_lshl_add_u64 v[224:225], s[48:49], 0, v[182:183]
	s_mov_b32 m0, s50
	v_lshl_add_u64 v[226:227], s[20:21], 0, v[130:131]
	global_load_lds_dwordx4 v[224:225], off
	v_lshl_add_u64 v[224:225], s[48:49], 0, v[128:129]
	s_add_i32 m0, s50, 0x2000
	s_nop 0
	global_load_lds_dwordx4 v[224:225], off
	v_lshl_add_u64 v[224:225], s[20:21], 0, v[132:133]
	s_mov_b32 m0, s26
	s_nop 0
	global_load_lds_dwordx4 v[224:225], off
	s_mov_b32 m0, s27
	s_nop 0
	global_load_lds_dwordx4 v[226:227], off
	s_waitcnt vmcnt(8)
	s_waitcnt lgkmcnt(0)
	s_barrier
; #define PG8_STAGE(bufoff, gbase, voff) do { _Pragma("unroll") for (int _i = 0; _i < 2; ++_i) \
;         __builtin_amdgcn_global_load_lds((const unsigned*)((const char*)(gbase) + (voff)[_i]), (PG8_LAS unsigned*)(lds + (bufoff) + ldsw + _i * 8192), 16, 0, 0); } while (0)
; #define PG8_LDA(dst, b, h) do { _Pragma("unroll") for (int m = 0; m < 4; ++m) _Pragma("unroll") for (int k = 0; k < 2; ++k) dst[m][k] = *(const PG8_LAS bf16x8*)(lds + PG8_SA(b, h) + aoff + m * 2048 + k * 1024); } while (0)
; #define PG8_LDB(dst, b, h) do { _Pragma("unroll") for (int n = 0; n < 2; ++n) _Pragma("unroll") for (int k = 0; k < 2; ++k) dst[n][k] = *(const PG8_LAS bf16x8*)(lds + PG8_SB(b, h) + boff + n * 2048 + k * 1024); } while (0)
; #define PG8_MMA(ai, bj, At, Bt) do { __builtin_amdgcn_s_setprio(1); _Pragma("unroll") for (int m = 0; m < 4; ++m) _Pragma("unroll") for (int n = 0; n < 2; ++n) _Pragma("unroll") for (int k = 0; k < 2; ++k) \
;         acc[ai][bj][m][n] = __builtin_amdgcn_mfma_f32_16x16x32_bf16(Bt[n][k], At[m][k], acc[ai][bj][m][n], 0, 0, 0); __builtin_amdgcn_s_setprio(0); } while (0)
; #define PG8_WAIT_V(n) asm volatile("s_waitcnt vmcnt(" #n ")" ::: "memory")
; #define PG8_WAIT_L(n) asm volatile("s_waitcnt lgkmcnt(" #n ")" ::: "memory")
; #define PG8_BAR __builtin_amdgcn_s_barrier()
; #define PG8_SCHED __builtin_amdgcn_sched_barrier(0)
; template <class Epi, class Sched, bool ALIGN_EPI = false, bool SP2 = false>
; __device__ __forceinline__ void gemm_phase(PG8_LAS unsigned char* lds, const Gemm g, const Sched& S, const Epi& E, const int wid_in) {
;     ...
;             PG8_WAIT_V(8); PG8_WAIT_L(0); PG8_BAR; PG8_MMA(1, 0, At, B0); PG8_MMA(1, 1, At, B1); PG8_BAR; PG8_SCHED;
;             PG8_LDB(B0, 1, 0); PG8_LDB(B1, 1, 1); PG8_SCHED; PG8_LDA(At, 1, 0); PG8_STAGE(PG8_SA(0, 1), a2 + hstep, voffA);
;             PG8_WAIT_V(8); PG8_WAIT_L(0); PG8_BAR; PG8_MMA(0, 0, At, B0); PG8_MMA(0, 1, At, B1); PG8_BAR; PG8_SCHED;
	s_setprio 1
	s_waitcnt lgkmcnt(0)
	v_mfma_f32_16x16x32_bf16 v[60:63], v[138:141], v[174:177], v[60:63]
	v_mfma_f32_16x16x32_bf16 v[56:59], v[150:153], v[174:177], v[56:59]
	v_mfma_f32_16x16x32_bf16 v[44:47], v[138:141], v[188:191], v[44:47]
	v_mfma_f32_16x16x32_bf16 v[40:43], v[150:153], v[188:191], v[40:43]
	v_mfma_f32_16x16x32_bf16 v[28:31], v[138:141], v[196:199], v[28:31]
	v_mfma_f32_16x16x32_bf16 v[24:27], v[150:153], v[196:199], v[24:27]
	v_mfma_f32_16x16x32_bf16 v[12:15], v[138:141], v[214:217], v[12:15]
	v_mfma_f32_16x16x32_bf16 v[8:11], v[150:153], v[214:217], v[8:11]
	v_mfma_f32_16x16x32_bf16 v[60:63], v[142:145], v[178:181], v[60:63]
	v_mfma_f32_16x16x32_bf16 v[56:59], v[154:157], v[178:181], v[56:59]
	v_mfma_f32_16x16x32_bf16 v[44:47], v[142:145], v[192:195], v[44:47]
	v_mfma_f32_16x16x32_bf16 v[40:43], v[154:157], v[192:195], v[40:43]
	v_mfma_f32_16x16x32_bf16 v[28:31], v[142:145], v[200:203], v[28:31]
	v_mfma_f32_16x16x32_bf16 v[24:27], v[154:157], v[200:203], v[24:27]
	v_mfma_f32_16x16x32_bf16 v[12:15], v[142:145], v[218:221], v[12:15]
	v_mfma_f32_16x16x32_bf16 v[8:11], v[154:157], v[218:221], v[8:11]
	s_setprio 0
	s_setprio 1
	v_mfma_f32_16x16x32_bf16 v[52:55], v[158:161], v[174:177], v[52:55]
	v_mfma_f32_16x16x32_bf16 v[48:51], v[166:169], v[174:177], v[48:51]
	v_mfma_f32_16x16x32_bf16 v[36:39], v[158:161], v[188:191], v[36:39]
	v_mfma_f32_16x16x32_bf16 v[32:35], v[166:169], v[188:191], v[32:35]
	v_mfma_f32_16x16x32_bf16 v[20:23], v[158:161], v[196:199], v[20:23]
	v_mfma_f32_16x16x32_bf16 v[16:19], v[166:169], v[196:199], v[16:19]
	v_mfma_f32_16x16x32_bf16 v[4:7], v[158:161], v[214:217], v[4:7]
	v_mfma_f32_16x16x32_bf16 v[0:3], v[166:169], v[214:217], v[0:3]
	v_mfma_f32_16x16x32_bf16 v[52:55], v[162:165], v[178:181], v[52:55]
	v_mfma_f32_16x16x32_bf16 v[48:51], v[170:173], v[178:181], v[48:51]
	v_mfma_f32_16x16x32_bf16 v[36:39], v[162:165], v[192:195], v[36:39]
	v_mfma_f32_16x16x32_bf16 v[32:35], v[170:173], v[192:195], v[32:35]
	v_mfma_f32_16x16x32_bf16 v[20:23], v[162:165], v[200:203], v[20:23]
	v_mfma_f32_16x16x32_bf16 v[16:19], v[170:173], v[200:203], v[16:19]
	v_mfma_f32_16x16x32_bf16 v[4:7], v[162:165], v[218:221], v[4:7]
	v_mfma_f32_16x16x32_bf16 v[0:3], v[170:173], v[218:221], v[0:3]
	s_setprio 0
	s_barrier
	s_add_i32 s48, 0, 0x18000
	s_add_i32 s49, 0, 0x1c000
	v_add_u32_e32 v154, s48, v147
	v_add_u32_e32 v170, s49, v147
	ds_read_b128 v[138:141], v154
	ds_read_b128 v[142:145], v154 offset:1024
	ds_read_b128 v[150:153], v154 offset:2048
	ds_read_b128 v[154:157], v154 offset:3072
	ds_read_b128 v[158:161], v170
	ds_read_b128 v[162:165], v170 offset:1024
	ds_read_b128 v[166:169], v170 offset:2048
	ds_read_b128 v[170:173], v170 offset:3072
	s_add_u32 s20, s20, 0x80000
	s_addc_u32 s21, s21, 0
	s_mov_b32 m0, s28
	v_lshl_add_u64 v[228:229], s[20:21], 0, v[132:133]
	ds_read_b128 v[174:177], v149 offset:32768
	ds_read_b128 v[178:181], v149 offset:33792
	ds_read_b128 v[188:191], v149 offset:34816
	ds_read_b128 v[192:195], v149 offset:35840
	ds_read_b128 v[196:199], v149 offset:36864
	ds_read_b128 v[200:203], v149 offset:37888
	ds_read_b128 v[214:217], v149 offset:38912
	ds_read_b128 v[218:221], v149 offset:39936
	global_load_lds_dwordx4 v[228:229], off
	v_lshl_add_u64 v[228:229], s[20:21], 0, v[130:131]
	s_mov_b32 m0, s29
	s_nop 0
	global_load_lds_dwordx4 v[228:229], off
	s_waitcnt vmcnt(8)
	s_waitcnt lgkmcnt(0)
	s_barrier
	s_setprio 1
	s_waitcnt lgkmcnt(0)
	v_mfma_f32_16x16x32_bf16 v[124:127], v[138:141], v[174:177], v[124:127]
	v_mfma_f32_16x16x32_bf16 v[120:123], v[150:153], v[174:177], v[120:123]
	v_mfma_f32_16x16x32_bf16 v[108:111], v[138:141], v[188:191], v[108:111]
	v_mfma_f32_16x16x32_bf16 v[104:107], v[150:153], v[188:191], v[104:107]
	v_mfma_f32_16x16x32_bf16 v[92:95], v[138:141], v[196:199], v[92:95]
	v_mfma_f32_16x16x32_bf16 v[88:91], v[150:153], v[196:199], v[88:91]
	v_mfma_f32_16x16x32_bf16 v[76:79], v[138:141], v[214:217], v[76:79]
	v_mfma_f32_16x16x32_bf16 v[72:75], v[150:153], v[214:217], v[72:75]
	v_mfma_f32_16x16x32_bf16 v[124:127], v[142:145], v[178:181], v[124:127]
	v_mfma_f32_16x16x32_bf16 v[120:123], v[154:157], v[178:181], v[120:123]
	v_mfma_f32_16x16x32_bf16 v[108:111], v[142:145], v[192:195], v[108:111]
	v_mfma_f32_16x16x32_bf16 v[104:107], v[154:157], v[192:195], v[104:107]
	v_mfma_f32_16x16x32_bf16 v[92:95], v[142:145], v[200:203], v[92:95]
	v_mfma_f32_16x16x32_bf16 v[88:91], v[154:157], v[200:203], v[88:91]
	v_mfma_f32_16x16x32_bf16 v[76:79], v[142:145], v[218:221], v[76:79]
	v_mfma_f32_16x16x32_bf16 v[72:75], v[154:157], v[218:221], v[72:75]
	s_setprio 0
	s_setprio 1
	v_mfma_f32_16x16x32_bf16 v[116:119], v[158:161], v[174:177], v[116:119]
	v_mfma_f32_16x16x32_bf16 v[112:115], v[166:169], v[174:177], v[112:115]
	v_mfma_f32_16x16x32_bf16 v[100:103], v[158:161], v[188:191], v[100:103]
	v_mfma_f32_16x16x32_bf16 v[96:99], v[166:169], v[188:191], v[96:99]
	v_mfma_f32_16x16x32_bf16 v[84:87], v[158:161], v[196:199], v[84:87]
	v_mfma_f32_16x16x32_bf16 v[80:83], v[166:169], v[196:199], v[80:83]
	v_mfma_f32_16x16x32_bf16 v[68:71], v[158:161], v[214:217], v[68:71]
	v_mfma_f32_16x16x32_bf16 v[64:67], v[166:169], v[214:217], v[64:67]
	v_mfma_f32_16x16x32_bf16 v[116:119], v[162:165], v[178:181], v[116:119]
	v_mfma_f32_16x16x32_bf16 v[112:115], v[170:173], v[178:181], v[112:115]
	v_mfma_f32_16x16x32_bf16 v[100:103], v[162:165], v[192:195], v[100:103]
	v_mfma_f32_16x16x32_bf16 v[96:99], v[170:173], v[192:195], v[96:99]
	v_mfma_f32_16x16x32_bf16 v[84:87], v[162:165], v[200:203], v[84:87]
	v_mfma_f32_16x16x32_bf16 v[80:83], v[170:173], v[200:203], v[80:83]
	v_mfma_f32_16x16x32_bf16 v[68:71], v[162:165], v[218:221], v[68:71]
	v_mfma_f32_16x16x32_bf16 v[64:67], v[170:173], v[218:221], v[64:67]
	s_setprio 0
	s_barrier
; #define PG8_STAGE(bufoff, gbase, voff) do { _Pragma("unroll") for (int _i = 0; _i < 2; ++_i) \
;         __builtin_amdgcn_global_load_lds((const unsigned*)((const char*)(gbase) + (voff)[_i]), (PG8_LAS unsigned*)(lds + (bufoff) + ldsw + _i * 8192), 16, 0, 0); } while (0)
; #define PG8_LDA(dst, b, h) do { _Pragma("unroll") for (int m = 0; m < 4; ++m) _Pragma("unroll") for (int k = 0; k < 2; ++k) dst[m][k] = *(const PG8_LAS bf16x8*)(lds + PG8_SA(b, h) + aoff + m * 2048 + k * 1024); } while (0)
; #define PG8_MMA(ai, bj, At, Bt) do { __builtin_amdgcn_s_setprio(1); _Pragma("unroll") for (int m = 0; m < 4; ++m) _Pragma("unroll") for (int n = 0; n < 2; ++n) _Pragma("unroll") for (int k = 0; k < 2; ++k) \
;         acc[ai][bj][m][n] = __builtin_amdgcn_mfma_f32_16x16x32_bf16(Bt[n][k], At[m][k], acc[ai][bj][m][n], 0, 0, 0); __builtin_amdgcn_s_setprio(0); } while (0)
; #define PG8_WAIT_V(n) asm volatile("s_waitcnt vmcnt(" #n ")" ::: "memory")
; #define PG8_WAIT_L(n) asm volatile("s_waitcnt lgkmcnt(" #n ")" ::: "memory")
; #define PG8_BAR __builtin_amdgcn_s_barrier()
; #define PG8_SCHED __builtin_amdgcn_sched_barrier(0)
; template <class Epi, class Sched, bool ALIGN_EPI = false, bool SP2 = false>
; __device__ __forceinline__ void gemm_phase(PG8_LAS unsigned char* lds, const Gemm g, const Sched& S, const Epi& E, const int wid_in) {
;     ...
;         for (int t = 0; t < nt; t += 2) {
;             const bool last = (t == nt - 2);
;             const char* a1 = cA + (size_t)(t + 1) * kstep;
;             const char* a2 = last ? nA : cA + (size_t)(t + 2) * kstep; const char* b2 = last ? nB : cB + (size_t)(t + 2) * kstep;
;             const char* a3 = a2 + kstep; const char* b3 = b2 + kstep;
;             if (last && has_next) S.a_ready(nxt);
;     ...
;             PG8_LDA(At, 1, 1); PG8_STAGE(PG8_SB(1, 0), b3, voffB); PG8_STAGE(PG8_SB(1, 1), b3 + hstep, voffB); PG8_STAGE(PG8_SA(1, 0), a3, voffA);
;             PG8_WAIT_V(8); PG8_WAIT_L(0); PG8_BAR; PG8_MMA(1, 0, At, B0); PG8_MMA(1, 1, At, B1); PG8_BAR; PG8_SCHED;
;     ...
;         if constexpr (ALIGN_EPI) { if (wr == 0) PG8_BAR; }
	s_add_i32 s20, s48, s25
	v_lshl_add_u64 v[204:205], v[204:205], 0, s[74:75]
	s_mov_b32 m0, s20
	ds_read_b128 v[174:177], v149 offset:49152
	ds_read_b128 v[178:181], v149 offset:50176
	ds_read_b128 v[188:191], v149 offset:51200
	ds_read_b128 v[192:195], v149 offset:52224
	ds_read_b128 v[196:199], v149 offset:53248
	ds_read_b128 v[200:203], v149 offset:54272
	ds_read_b128 v[214:217], v149 offset:55296
	ds_read_b128 v[218:221], v149 offset:56320
	global_load_lds_dwordx4 v[204:205], off
	s_add_i32 m0, s20, 0x2000
	s_add_u32 s18, s18, 0x80080
	v_lshl_add_u64 v[204:205], v[222:223], 0, s[74:75]
	s_addc_u32 s19, s19, 0
	s_add_i32 s20, s49, s25
	global_load_lds_dwordx4 v[204:205], off
	v_lshl_add_u64 v[204:205], s[18:19], 0, v[182:183]
	s_mov_b32 m0, s20
	s_nop 0
	global_load_lds_dwordx4 v[204:205], off
	v_lshl_add_u64 v[204:205], s[18:19], 0, v[128:129]
	s_add_i32 m0, s20, 0x2000
	s_nop 0
	global_load_lds_dwordx4 v[204:205], off
	v_lshl_add_u64 v[204:205], v[224:225], 0, s[74:75]
	s_mov_b32 m0, s36
	s_nop 0
	global_load_lds_dwordx4 v[204:205], off
	v_lshl_add_u64 v[204:205], v[226:227], 0, s[74:75]
	s_mov_b32 m0, s37
	s_nop 0
	global_load_lds_dwordx4 v[204:205], off
	s_waitcnt vmcnt(8)
	s_waitcnt lgkmcnt(0)
	s_barrier
	s_setprio 1
	s_waitcnt lgkmcnt(0)
	v_mfma_f32_16x16x32_bf16 v[60:63], v[138:141], v[174:177], v[60:63]
	v_mfma_f32_16x16x32_bf16 v[56:59], v[150:153], v[174:177], v[56:59]
	v_mfma_f32_16x16x32_bf16 v[44:47], v[138:141], v[188:191], v[44:47]
	v_mfma_f32_16x16x32_bf16 v[40:43], v[150:153], v[188:191], v[40:43]
	v_mfma_f32_16x16x32_bf16 v[28:31], v[138:141], v[196:199], v[28:31]
	v_mfma_f32_16x16x32_bf16 v[24:27], v[150:153], v[196:199], v[24:27]
	v_mfma_f32_16x16x32_bf16 v[12:15], v[138:141], v[214:217], v[12:15]
	v_mfma_f32_16x16x32_bf16 v[8:11], v[150:153], v[214:217], v[8:11]
	v_mfma_f32_16x16x32_bf16 v[60:63], v[142:145], v[178:181], v[60:63]
	v_mfma_f32_16x16x32_bf16 v[56:59], v[154:157], v[178:181], v[56:59]
	v_mfma_f32_16x16x32_bf16 v[44:47], v[142:145], v[192:195], v[44:47]
	v_mfma_f32_16x16x32_bf16 v[40:43], v[154:157], v[192:195], v[40:43]
	v_mfma_f32_16x16x32_bf16 v[28:31], v[142:145], v[200:203], v[28:31]
	v_mfma_f32_16x16x32_bf16 v[24:27], v[154:157], v[200:203], v[24:27]
	v_mfma_f32_16x16x32_bf16 v[12:15], v[142:145], v[218:221], v[12:15]
	v_mfma_f32_16x16x32_bf16 v[8:11], v[154:157], v[218:221], v[8:11]
	s_setprio 0
	s_setprio 1
	v_mfma_f32_16x16x32_bf16 v[52:55], v[158:161], v[174:177], v[52:55]
	v_mfma_f32_16x16x32_bf16 v[48:51], v[166:169], v[174:177], v[48:51]
	v_mfma_f32_16x16x32_bf16 v[36:39], v[158:161], v[188:191], v[36:39]
	v_mfma_f32_16x16x32_bf16 v[32:35], v[166:169], v[188:191], v[32:35]
	v_mfma_f32_16x16x32_bf16 v[20:23], v[158:161], v[196:199], v[20:23]
	v_mfma_f32_16x16x32_bf16 v[16:19], v[166:169], v[196:199], v[16:19]
	v_mfma_f32_16x16x32_bf16 v[4:7], v[158:161], v[214:217], v[4:7]
	v_mfma_f32_16x16x32_bf16 v[0:3], v[166:169], v[214:217], v[0:3]
	v_mfma_f32_16x16x32_bf16 v[52:55], v[162:165], v[178:181], v[52:55]
	v_mfma_f32_16x16x32_bf16 v[48:51], v[170:173], v[178:181], v[48:51]
	v_mfma_f32_16x16x32_bf16 v[36:39], v[162:165], v[192:195], v[36:39]
	v_mfma_f32_16x16x32_bf16 v[32:35], v[170:173], v[192:195], v[32:35]
	v_mfma_f32_16x16x32_bf16 v[20:23], v[162:165], v[200:203], v[20:23]
	v_mfma_f32_16x16x32_bf16 v[16:19], v[170:173], v[200:203], v[16:19]
	v_mfma_f32_16x16x32_bf16 v[4:7], v[162:165], v[218:221], v[4:7]
	v_mfma_f32_16x16x32_bf16 v[0:3], v[170:173], v[218:221], v[0:3]
	s_setprio 0
	s_add_i32 s47, s47, 2
	s_add_u32 s4, s4, 0x100
	s_addc_u32 s5, s5, 0
	s_add_u32 s45, s45, 0x100
	s_addc_u32 s46, s46, 0
	s_cmp_gt_u32 s47, 29
	s_cbranch_scc1 .Lrot_x_1212
	s_add_u32 s18, s4, 0xfff80080
	s_addc_u32 s19, s5, -1
	s_add_i32 s48, 0, 0x10000
	s_cmp_eq_u32 s47, 28
	s_cselect_b32 s21, s13, s19
	s_cselect_b32 s20, s43, s18
	s_cselect_b32 s19, s11, s46
	s_cselect_b32 s18, s44, s45
	s_add_i32 s50, 0, 0x14000
	s_barrier
	s_branch .Lrot_h_1212
.Lrot_x_1212:
	s_barrier
	s_and_b64 vcc, exec, s[8:9]
	s_cbranch_vccz .LBB0_1215
	s_barrier

; #define PG8_STAGE(bufoff, gbase, voff) do { _Pragma("unroll") for (int _i = 0; _i < 2; ++_i) \
;         __builtin_amdgcn_global_load_lds((const unsigned*)((const char*)(gbase) + (voff)[_i]), (PG8_LAS unsigned*)(lds + (bufoff) + ldsw + _i * 8192), 16, 0, 0); } while (0)
; #define PG8_LDA(dst, b, h) do { _Pragma("unroll") for (int m = 0; m < 4; ++m) _Pragma("unroll") for (int k = 0; k < 2; ++k) dst[m][k] = *(const PG8_LAS bf16x8*)(lds + PG8_SA(b, h) + aoff + m * 2048 + k * 1024); } while (0)
; #define PG8_LDB(dst, b, h) do { _Pragma("unroll") for (int n = 0; n < 2; ++n) _Pragma("unroll") for (int k = 0; k < 2; ++k) dst[n][k] = *(const PG8_LAS bf16x8*)(lds + PG8_SB(b, h) + boff + n * 2048 + k * 1024); } while (0)
; #define PG8_MMA(ai, bj, At, Bt) do { __builtin_amdgcn_s_setprio(1); _Pragma("unroll") for (int m = 0; m < 4; ++m) _Pragma("unroll") for (int n = 0; n < 2; ++n) _Pragma("unroll") for (int k = 0; k < 2; ++k) \
;         acc[ai][bj][m][n] = __builtin_amdgcn_mfma_f32_16x16x32_bf16(Bt[n][k], At[m][k], acc[ai][bj][m][n], 0, 0, 0); __builtin_amdgcn_s_setprio(0); } while (0)
; #define PG8_WAIT_V(n) asm volatile("s_waitcnt vmcnt(" #n ")" ::: "memory")
; #define PG8_WAIT_L(n) asm volatile("s_waitcnt lgkmcnt(" #n ")" ::: "memory")
; #define PG8_BAR __builtin_amdgcn_s_barrier()
; template <class Epi, class Sched, bool ALIGN_EPI = false, bool SP2 = false>
; __device__ __forceinline__ void gemm_phase(PG8_LAS unsigned char* lds, const Gemm g, const Sched& S, const Epi& E, const int wid_in) {
;     ...
;         for (int t = 0; t < nt; t += 2) {
;             const bool last = (t == nt - 2);
;             const char* a1 = cA + (size_t)(t + 1) * kstep;
;             const char* a2 = last ? nA : cA + (size_t)(t + 2) * kstep; const char* b2 = last ? nB : cB + (size_t)(t + 2) * kstep;
;             const char* a3 = a2 + kstep; const char* b3 = b2 + kstep;
;             if (last && has_next) S.a_ready(nxt);
;             if constexpr (SP2) {
;             PG8_LDB(B0, 0, 0); PG8_LDB(B1, 0, 1); PG8_SCHED; PG8_LDA(At, 0, 0); PG8_STAGE(PG8_SA(1, 1), a1 + hstep, voffA);
;             PG8_WAIT_V(8); PG8_WAIT_L(0); PG8_BAR; PG8_MMA(0, 0, At, B0); PG8_MMA(0, 1, At, B1); PG8_BAR; PG8_SCHED;
;             PG8_LDA(At, 0, 1); PG8_STAGE(PG8_SB(0, 0), b2, voffB); PG8_STAGE(PG8_SB(0, 1), b2 + hstep, voffB); PG8_STAGE(PG8_SA(0, 0), a2, voffA);
.Lrot_h_1269:
	v_add_u32_e32 v88, s54, v215
	v_add_u32_e32 v156, s55, v215
	ds_read_b128 v[72:75], v88
	ds_read_b128 v[80:83], v88 offset:1024
	ds_read_b128 v[84:87], v88 offset:2048
	ds_read_b128 v[88:91], v88 offset:3072
	ds_read_b128 v[144:147], v156
	ds_read_b128 v[148:151], v156 offset:1024
	ds_read_b128 v[152:155], v156 offset:2048
	ds_read_b128 v[156:159], v156 offset:3072
	v_lshl_add_u64 v[180:181], s[4:5], 0, v[192:193]
	s_add_i32 m0, s40, 0xc000
	ds_read_b128 v[160:163], v219
	ds_read_b128 v[164:167], v219 offset:1024
	ds_read_b128 v[168:171], v219 offset:2048
	ds_read_b128 v[172:175], v219 offset:3072
	ds_read_b128 v[176:179], v219 offset:4096
	ds_read_b128 v[196:199], v219 offset:5120
	ds_read_b128 v[200:203], v219 offset:6144
	ds_read_b128 v[220:223], v219 offset:7168
	global_load_lds_dwordx4 v[180:181], off
	v_lshl_add_u64 v[180:181], s[4:5], 0, v[194:195]
	s_add_i32 m0, s40, 0xe000
	s_nop 0
	global_load_lds_dwordx4 v[180:181], off
	s_waitcnt vmcnt(8)
	s_waitcnt lgkmcnt(0)
	s_barrier
	s_setprio 1
	s_waitcnt lgkmcnt(0)
	v_mfma_f32_16x16x32_bf16 v[140:143], v[72:75], v[160:163], v[140:143]
	v_mfma_f32_16x16x32_bf16 v[136:139], v[84:87], v[160:163], v[136:139]
	v_mfma_f32_16x16x32_bf16 v[128:131], v[72:75], v[168:171], v[128:131]
	v_mfma_f32_16x16x32_bf16 v[120:123], v[84:87], v[168:171], v[120:123]
	v_mfma_f32_16x16x32_bf16 v[112:115], v[72:75], v[176:179], v[112:115]
	v_mfma_f32_16x16x32_bf16 v[104:107], v[84:87], v[176:179], v[104:107]
	v_mfma_f32_16x16x32_bf16 v[96:99], v[72:75], v[200:203], v[96:99]
	v_mfma_f32_16x16x32_bf16 v[76:79], v[84:87], v[200:203], v[76:79]
	v_mfma_f32_16x16x32_bf16 v[140:143], v[80:83], v[164:167], v[140:143]
	v_mfma_f32_16x16x32_bf16 v[136:139], v[88:91], v[164:167], v[136:139]
	v_mfma_f32_16x16x32_bf16 v[128:131], v[80:83], v[172:175], v[128:131]
	v_mfma_f32_16x16x32_bf16 v[120:123], v[88:91], v[172:175], v[120:123]
	v_mfma_f32_16x16x32_bf16 v[112:115], v[80:83], v[196:199], v[112:115]
	v_mfma_f32_16x16x32_bf16 v[104:107], v[88:91], v[196:199], v[104:107]
	v_mfma_f32_16x16x32_bf16 v[96:99], v[80:83], v[220:223], v[96:99]
	v_mfma_f32_16x16x32_bf16 v[76:79], v[88:91], v[220:223], v[76:79]
	s_setprio 0
	s_setprio 1
	v_mfma_f32_16x16x32_bf16 v[132:135], v[144:147], v[160:163], v[132:135]
	v_mfma_f32_16x16x32_bf16 v[124:127], v[152:155], v[160:163], v[124:127]
	v_mfma_f32_16x16x32_bf16 v[116:119], v[144:147], v[168:171], v[116:119]
	v_mfma_f32_16x16x32_bf16 v[108:111], v[152:155], v[168:171], v[108:111]
	v_mfma_f32_16x16x32_bf16 v[100:103], v[144:147], v[176:179], v[100:103]
	v_mfma_f32_16x16x32_bf16 v[92:95], v[152:155], v[176:179], v[92:95]
	v_mfma_f32_16x16x32_bf16 v[68:71], v[144:147], v[200:203], v[68:71]
	v_mfma_f32_16x16x32_bf16 v[64:67], v[152:155], v[200:203], v[64:67]
	v_mfma_f32_16x16x32_bf16 v[132:135], v[148:151], v[164:167], v[132:135]
	v_mfma_f32_16x16x32_bf16 v[124:127], v[156:159], v[164:167], v[124:127]
	v_mfma_f32_16x16x32_bf16 v[116:119], v[148:151], v[172:175], v[116:119]
	v_mfma_f32_16x16x32_bf16 v[108:111], v[156:159], v[172:175], v[108:111]
	v_mfma_f32_16x16x32_bf16 v[100:103], v[148:151], v[196:199], v[100:103]
	v_mfma_f32_16x16x32_bf16 v[92:95], v[156:159], v[196:199], v[92:95]
	v_mfma_f32_16x16x32_bf16 v[68:71], v[148:151], v[220:223], v[68:71]
	v_mfma_f32_16x16x32_bf16 v[64:67], v[156:159], v[220:223], v[64:67]
	s_setprio 0
	s_barrier
	s_add_i32 s4, s54, s39
	v_lshl_add_u64 v[180:181], s[26:27], 0, v[182:183]
	s_mov_b32 m0, s4
	ds_read_b128 v[160:163], v219 offset:16384
	ds_read_b128 v[164:167], v219 offset:17408
	ds_read_b128 v[168:171], v219 offset:18432
	ds_read_b128 v[172:175], v219 offset:19456
	ds_read_b128 v[176:179], v219 offset:20480
	ds_read_b128 v[196:199], v219 offset:21504
	ds_read_b128 v[200:203], v219 offset:22528
	ds_read_b128 v[220:223], v219 offset:23552
	global_load_lds_dwordx4 v[180:181], off
	s_add_i32 m0, s4, 0x2000
	s_add_u32 s4, s26, 0x200000
	v_lshl_add_u64 v[188:189], s[26:27], 0, v[190:191]
	s_addc_u32 s5, s27, 0
	s_add_i32 s54, s55, s39
	global_load_lds_dwordx4 v[188:189], off
	v_lshl_add_u64 v[204:205], s[4:5], 0, v[182:183]
	s_mov_b32 m0, s54
	v_lshl_add_u64 v[224:225], s[28:29], 0, v[190:191]
	global_load_lds_dwordx4 v[204:205], off
	v_lshl_add_u64 v[204:205], s[4:5], 0, v[190:191]
	s_add_i32 m0, s54, 0x2000
	s_nop 0
	global_load_lds_dwordx4 v[204:205], off
	v_lshl_add_u64 v[204:205], s[28:29], 0, v[182:183]
	s_mov_b32 m0, s40
	s_nop 0
	global_load_lds_dwordx4 v[204:205], off
	s_mov_b32 m0, s41
	s_nop 0
	global_load_lds_dwordx4 v[224:225], off
	s_waitcnt vmcnt(8)
	s_waitcnt lgkmcnt(0)
	s_barrier
; #define PG8_STAGE(bufoff, gbase, voff) do { _Pragma("unroll") for (int _i = 0; _i < 2; ++_i) \
;         __builtin_amdgcn_global_load_lds((const unsigned*)((const char*)(gbase) + (voff)[_i]), (PG8_LAS unsigned*)(lds + (bufoff) + ldsw + _i * 8192), 16, 0, 0); } while (0)
; #define PG8_LDA(dst, b, h) do { _Pragma("unroll") for (int m = 0; m < 4; ++m) _Pragma("unroll") for (int k = 0; k < 2; ++k) dst[m][k] = *(const PG8_LAS bf16x8*)(lds + PG8_SA(b, h) + aoff + m * 2048 + k * 1024); } while (0)
; #define PG8_LDB(dst, b, h) do { _Pragma("unroll") for (int n = 0; n < 2; ++n) _Pragma("unroll") for (int k = 0; k < 2; ++k) dst[n][k] = *(const PG8_LAS bf16x8*)(lds + PG8_SB(b, h) + boff + n * 2048 + k * 1024); } while (0)
; #define PG8_MMA(ai, bj, At, Bt) do { __builtin_amdgcn_s_setprio(1); _Pragma("unroll") for (int m = 0; m < 4; ++m) _Pragma("unroll") for (int n = 0; n < 2; ++n) _Pragma("unroll") for (int k = 0; k < 2; ++k) \
;         acc[ai][bj][m][n] = __builtin_amdgcn_mfma_f32_16x16x32_bf16(Bt[n][k], At[m][k], acc[ai][bj][m][n], 0, 0, 0); __builtin_amdgcn_s_setprio(0); } while (0)
; #define PG8_WAIT_V(n) asm volatile("s_waitcnt vmcnt(" #n ")" ::: "memory")
; #define PG8_WAIT_L(n) asm volatile("s_waitcnt lgkmcnt(" #n ")" ::: "memory")
; #define PG8_BAR __builtin_amdgcn_s_barrier()
; #define PG8_SCHED __builtin_amdgcn_sched_barrier(0)
; template <class Epi, class Sched, bool ALIGN_EPI = false, bool SP2 = false>
; __device__ __forceinline__ void gemm_phase(PG8_LAS unsigned char* lds, const Gemm g, const Sched& S, const Epi& E, const int wid_in) {
;     ...
;             PG8_WAIT_V(8); PG8_WAIT_L(0); PG8_BAR; PG8_MMA(1, 0, At, B0); PG8_MMA(1, 1, At, B1); PG8_BAR; PG8_SCHED;
;             PG8_LDB(B0, 1, 0); PG8_LDB(B1, 1, 1); PG8_SCHED; PG8_LDA(At, 1, 0); PG8_STAGE(PG8_SA(0, 1), a2 + hstep, voffA);
;             PG8_WAIT_V(8); PG8_WAIT_L(0); PG8_BAR; PG8_MMA(0, 0, At, B0); PG8_MMA(0, 1, At, B1); PG8_BAR; PG8_SCHED;
	s_setprio 1
	s_waitcnt lgkmcnt(0)
	v_mfma_f32_16x16x32_bf16 v[60:63], v[72:75], v[160:163], v[60:63]
	v_mfma_f32_16x16x32_bf16 v[56:59], v[84:87], v[160:163], v[56:59]
	v_mfma_f32_16x16x32_bf16 v[48:51], v[72:75], v[168:171], v[48:51]
	v_mfma_f32_16x16x32_bf16 v[40:43], v[84:87], v[168:171], v[40:43]
	v_mfma_f32_16x16x32_bf16 v[32:35], v[72:75], v[176:179], v[32:35]
	v_mfma_f32_16x16x32_bf16 v[24:27], v[84:87], v[176:179], v[24:27]
	v_mfma_f32_16x16x32_bf16 v[20:23], v[72:75], v[200:203], v[20:23]
	v_mfma_f32_16x16x32_bf16 v[8:11], v[84:87], v[200:203], v[8:11]
	v_mfma_f32_16x16x32_bf16 v[60:63], v[80:83], v[164:167], v[60:63]
	v_mfma_f32_16x16x32_bf16 v[56:59], v[88:91], v[164:167], v[56:59]
	v_mfma_f32_16x16x32_bf16 v[48:51], v[80:83], v[172:175], v[48:51]
	v_mfma_f32_16x16x32_bf16 v[40:43], v[88:91], v[172:175], v[40:43]
	v_mfma_f32_16x16x32_bf16 v[32:35], v[80:83], v[196:199], v[32:35]
	v_mfma_f32_16x16x32_bf16 v[24:27], v[88:91], v[196:199], v[24:27]
	v_mfma_f32_16x16x32_bf16 v[20:23], v[80:83], v[220:223], v[20:23]
	v_mfma_f32_16x16x32_bf16 v[8:11], v[88:91], v[220:223], v[8:11]
	s_setprio 0
	s_setprio 1
	v_mfma_f32_16x16x32_bf16 v[52:55], v[144:147], v[160:163], v[52:55]
	v_mfma_f32_16x16x32_bf16 v[44:47], v[152:155], v[160:163], v[44:47]
	v_mfma_f32_16x16x32_bf16 v[36:39], v[144:147], v[168:171], v[36:39]
	v_mfma_f32_16x16x32_bf16 v[28:31], v[152:155], v[168:171], v[28:31]
	v_mfma_f32_16x16x32_bf16 v[16:19], v[144:147], v[176:179], v[16:19]
	v_mfma_f32_16x16x32_bf16 v[12:15], v[152:155], v[176:179], v[12:15]
	v_mfma_f32_16x16x32_bf16 v[4:7], v[144:147], v[200:203], v[4:7]
	v_mfma_f32_16x16x32_bf16 v[0:3], v[152:155], v[200:203], v[0:3]
	v_mfma_f32_16x16x32_bf16 v[52:55], v[148:151], v[164:167], v[52:55]
	v_mfma_f32_16x16x32_bf16 v[44:47], v[156:159], v[164:167], v[44:47]
	v_mfma_f32_16x16x32_bf16 v[36:39], v[148:151], v[172:175], v[36:39]
	v_mfma_f32_16x16x32_bf16 v[28:31], v[156:159], v[172:175], v[28:31]
	v_mfma_f32_16x16x32_bf16 v[16:19], v[148:151], v[196:199], v[16:19]
	v_mfma_f32_16x16x32_bf16 v[12:15], v[156:159], v[196:199], v[12:15]
	v_mfma_f32_16x16x32_bf16 v[4:7], v[148:151], v[220:223], v[4:7]
	v_mfma_f32_16x16x32_bf16 v[0:3], v[156:159], v[220:223], v[0:3]
	s_setprio 0
	s_barrier
	s_add_i32 s54, 0, 0x18000
	s_add_i32 s55, 0, 0x1c000
	v_add_u32_e32 v88, s54, v215
	v_add_u32_e32 v156, s55, v215
	ds_read_b128 v[72:75], v88
	ds_read_b128 v[80:83], v88 offset:1024
	ds_read_b128 v[84:87], v88 offset:2048
	ds_read_b128 v[88:91], v88 offset:3072
	ds_read_b128 v[144:147], v156
	ds_read_b128 v[148:151], v156 offset:1024
	ds_read_b128 v[152:155], v156 offset:2048
	ds_read_b128 v[156:159], v156 offset:3072
	s_add_u32 s4, s28, 0x200000
	s_addc_u32 s5, s29, 0
	s_mov_b32 m0, s42
	v_lshl_add_u64 v[226:227], s[4:5], 0, v[182:183]
	ds_read_b128 v[160:163], v219 offset:32768
	ds_read_b128 v[164:167], v219 offset:33792
	ds_read_b128 v[168:171], v219 offset:34816
	ds_read_b128 v[172:175], v219 offset:35840
	ds_read_b128 v[176:179], v219 offset:36864
	ds_read_b128 v[196:199], v219 offset:37888
	ds_read_b128 v[200:203], v219 offset:38912
	ds_read_b128 v[220:223], v219 offset:39936
	global_load_lds_dwordx4 v[226:227], off
	v_lshl_add_u64 v[226:227], s[4:5], 0, v[190:191]
	s_mov_b32 m0, s43
	s_nop 0
	global_load_lds_dwordx4 v[226:227], off
	s_waitcnt vmcnt(8)
	s_waitcnt lgkmcnt(0)
	s_barrier
	s_setprio 1
	s_waitcnt lgkmcnt(0)
	v_mfma_f32_16x16x32_bf16 v[140:143], v[72:75], v[160:163], v[140:143]
	v_mfma_f32_16x16x32_bf16 v[136:139], v[84:87], v[160:163], v[136:139]
	v_mfma_f32_16x16x32_bf16 v[128:131], v[72:75], v[168:171], v[128:131]
	v_mfma_f32_16x16x32_bf16 v[120:123], v[84:87], v[168:171], v[120:123]
	v_mfma_f32_16x16x32_bf16 v[112:115], v[72:75], v[176:179], v[112:115]
	v_mfma_f32_16x16x32_bf16 v[104:107], v[84:87], v[176:179], v[104:107]
	v_mfma_f32_16x16x32_bf16 v[96:99], v[72:75], v[200:203], v[96:99]
	v_mfma_f32_16x16x32_bf16 v[76:79], v[84:87], v[200:203], v[76:79]
	v_mfma_f32_16x16x32_bf16 v[140:143], v[80:83], v[164:167], v[140:143]
	v_mfma_f32_16x16x32_bf16 v[136:139], v[88:91], v[164:167], v[136:139]
	v_mfma_f32_16x16x32_bf16 v[128:131], v[80:83], v[172:175], v[128:131]
	v_mfma_f32_16x16x32_bf16 v[120:123], v[88:91], v[172:175], v[120:123]
	v_mfma_f32_16x16x32_bf16 v[112:115], v[80:83], v[196:199], v[112:115]
	v_mfma_f32_16x16x32_bf16 v[104:107], v[88:91], v[196:199], v[104:107]
	v_mfma_f32_16x16x32_bf16 v[96:99], v[80:83], v[220:223], v[96:99]
	v_mfma_f32_16x16x32_bf16 v[76:79], v[88:91], v[220:223], v[76:79]
	s_setprio 0
	s_setprio 1
	v_mfma_f32_16x16x32_bf16 v[132:135], v[144:147], v[160:163], v[132:135]
	v_mfma_f32_16x16x32_bf16 v[124:127], v[152:155], v[160:163], v[124:127]
	v_mfma_f32_16x16x32_bf16 v[116:119], v[144:147], v[168:171], v[116:119]
	v_mfma_f32_16x16x32_bf16 v[108:111], v[152:155], v[168:171], v[108:111]
	v_mfma_f32_16x16x32_bf16 v[100:103], v[144:147], v[176:179], v[100:103]
	v_mfma_f32_16x16x32_bf16 v[92:95], v[152:155], v[176:179], v[92:95]
	v_mfma_f32_16x16x32_bf16 v[68:71], v[144:147], v[200:203], v[68:71]
	v_mfma_f32_16x16x32_bf16 v[64:67], v[152:155], v[200:203], v[64:67]
	v_mfma_f32_16x16x32_bf16 v[132:135], v[148:151], v[164:167], v[132:135]
	v_mfma_f32_16x16x32_bf16 v[124:127], v[156:159], v[164:167], v[124:127]
	v_mfma_f32_16x16x32_bf16 v[116:119], v[148:151], v[172:175], v[116:119]
	v_mfma_f32_16x16x32_bf16 v[108:111], v[156:159], v[172:175], v[108:111]
	v_mfma_f32_16x16x32_bf16 v[100:103], v[148:151], v[196:199], v[100:103]
	v_mfma_f32_16x16x32_bf16 v[92:95], v[156:159], v[196:199], v[92:95]
	v_mfma_f32_16x16x32_bf16 v[68:71], v[148:151], v[220:223], v[68:71]
	v_mfma_f32_16x16x32_bf16 v[64:67], v[156:159], v[220:223], v[64:67]
	s_setprio 0
	s_barrier
; #define PG8_STAGE(bufoff, gbase, voff) do { _Pragma("unroll") for (int _i = 0; _i < 2; ++_i) \
;         __builtin_amdgcn_global_load_lds((const unsigned*)((const char*)(gbase) + (voff)[_i]), (PG8_LAS unsigned*)(lds + (bufoff) + ldsw + _i * 8192), 16, 0, 0); } while (0)
; #define PG8_LDA(dst, b, h) do { _Pragma("unroll") for (int m = 0; m < 4; ++m) _Pragma("unroll") for (int k = 0; k < 2; ++k) dst[m][k] = *(const PG8_LAS bf16x8*)(lds + PG8_SA(b, h) + aoff + m * 2048 + k * 1024); } while (0)
; #define PG8_MMA(ai, bj, At, Bt) do { __builtin_amdgcn_s_setprio(1); _Pragma("unroll") for (int m = 0; m < 4; ++m) _Pragma("unroll") for (int n = 0; n < 2; ++n) _Pragma("unroll") for (int k = 0; k < 2; ++k) \
;         acc[ai][bj][m][n] = __builtin_amdgcn_mfma_f32_16x16x32_bf16(Bt[n][k], At[m][k], acc[ai][bj][m][n], 0, 0, 0); __builtin_amdgcn_s_setprio(0); } while (0)
; #define PG8_WAIT_V(n) asm volatile("s_waitcnt vmcnt(" #n ")" ::: "memory")
; #define PG8_WAIT_L(n) asm volatile("s_waitcnt lgkmcnt(" #n ")" ::: "memory")
; #define PG8_BAR __builtin_amdgcn_s_barrier()
; #define PG8_SCHED __builtin_amdgcn_sched_barrier(0)
; template <class Epi, class Sched, bool ALIGN_EPI = false, bool SP2 = false>
; __device__ __forceinline__ void gemm_phase(PG8_LAS unsigned char* lds, const Gemm g, const Sched& S, const Epi& E, const int wid_in) {
;     ...
;         for (int t = 0; t < nt; t += 2) {
;             const bool last = (t == nt - 2);
;             const char* a1 = cA + (size_t)(t + 1) * kstep;
;             const char* a2 = last ? nA : cA + (size_t)(t + 2) * kstep; const char* b2 = last ? nB : cB + (size_t)(t + 2) * kstep;
;             const char* a3 = a2 + kstep; const char* b3 = b2 + kstep;
;             if (last && has_next) S.a_ready(nxt);
;     ...
;             PG8_LDA(At, 1, 1); PG8_STAGE(PG8_SB(1, 0), b3, voffB); PG8_STAGE(PG8_SB(1, 1), b3 + hstep, voffB); PG8_STAGE(PG8_SA(1, 0), a3, voffA);
;             PG8_WAIT_V(8); PG8_WAIT_L(0); PG8_BAR; PG8_MMA(1, 0, At, B0); PG8_MMA(1, 1, At, B1); PG8_BAR; PG8_SCHED;
	s_add_i32 s4, s54, s39
	v_lshl_add_u64 v[180:181], v[180:181], 0, s[74:75]
	s_mov_b32 m0, s4
	ds_read_b128 v[160:163], v219 offset:49152
	ds_read_b128 v[164:167], v219 offset:50176
	ds_read_b128 v[168:171], v219 offset:51200
	ds_read_b128 v[172:175], v219 offset:52224
	ds_read_b128 v[176:179], v219 offset:53248
	ds_read_b128 v[196:199], v219 offset:54272
	ds_read_b128 v[200:203], v219 offset:55296
	ds_read_b128 v[220:223], v219 offset:56320
	global_load_lds_dwordx4 v[180:181], off
	s_add_i32 m0, s4, 0x2000
	s_add_u32 s4, s26, 0x200080
	v_lshl_add_u64 v[180:181], v[188:189], 0, s[74:75]
	s_addc_u32 s5, s27, 0
	s_add_i32 s26, s55, s39
	global_load_lds_dwordx4 v[180:181], off
	v_lshl_add_u64 v[180:181], s[4:5], 0, v[182:183]
	s_mov_b32 m0, s26
	s_nop 0
	global_load_lds_dwordx4 v[180:181], off
	v_lshl_add_u64 v[180:181], s[4:5], 0, v[190:191]
	s_add_i32 m0, s26, 0x2000
	s_nop 0
	global_load_lds_dwordx4 v[180:181], off
	v_lshl_add_u64 v[180:181], v[204:205], 0, s[74:75]
	s_mov_b32 m0, s45
	s_nop 0
	global_load_lds_dwordx4 v[180:181], off
	v_lshl_add_u64 v[180:181], v[224:225], 0, s[74:75]
	s_mov_b32 m0, s46
	s_nop 0
	global_load_lds_dwordx4 v[180:181], off
	s_waitcnt vmcnt(8)
	s_waitcnt lgkmcnt(0)
	s_barrier
	s_setprio 1
	s_waitcnt lgkmcnt(0)
	v_mfma_f32_16x16x32_bf16 v[60:63], v[72:75], v[160:163], v[60:63]
	v_mfma_f32_16x16x32_bf16 v[56:59], v[84:87], v[160:163], v[56:59]
	v_mfma_f32_16x16x32_bf16 v[48:51], v[72:75], v[168:171], v[48:51]
	v_mfma_f32_16x16x32_bf16 v[40:43], v[84:87], v[168:171], v[40:43]
	v_mfma_f32_16x16x32_bf16 v[32:35], v[72:75], v[176:179], v[32:35]
	v_mfma_f32_16x16x32_bf16 v[24:27], v[84:87], v[176:179], v[24:27]
	v_mfma_f32_16x16x32_bf16 v[20:23], v[72:75], v[200:203], v[20:23]
	v_mfma_f32_16x16x32_bf16 v[8:11], v[84:87], v[200:203], v[8:11]
	v_mfma_f32_16x16x32_bf16 v[60:63], v[80:83], v[164:167], v[60:63]
	v_mfma_f32_16x16x32_bf16 v[56:59], v[88:91], v[164:167], v[56:59]
	v_mfma_f32_16x16x32_bf16 v[48:51], v[80:83], v[172:175], v[48:51]
	v_mfma_f32_16x16x32_bf16 v[40:43], v[88:91], v[172:175], v[40:43]
	v_mfma_f32_16x16x32_bf16 v[32:35], v[80:83], v[196:199], v[32:35]
	v_mfma_f32_16x16x32_bf16 v[24:27], v[88:91], v[196:199], v[24:27]
	v_mfma_f32_16x16x32_bf16 v[20:23], v[80:83], v[220:223], v[20:23]
	v_mfma_f32_16x16x32_bf16 v[8:11], v[88:91], v[220:223], v[8:11]
	s_setprio 0
	s_setprio 1
	v_mfma_f32_16x16x32_bf16 v[52:55], v[144:147], v[160:163], v[52:55]
	v_mfma_f32_16x16x32_bf16 v[44:47], v[152:155], v[160:163], v[44:47]
	v_mfma_f32_16x16x32_bf16 v[36:39], v[144:147], v[168:171], v[36:39]
	v_mfma_f32_16x16x32_bf16 v[28:31], v[152:155], v[168:171], v[28:31]
	v_mfma_f32_16x16x32_bf16 v[16:19], v[144:147], v[176:179], v[16:19]
	v_mfma_f32_16x16x32_bf16 v[12:15], v[152:155], v[176:179], v[12:15]
	v_mfma_f32_16x16x32_bf16 v[4:7], v[144:147], v[200:203], v[4:7]
	v_mfma_f32_16x16x32_bf16 v[0:3], v[152:155], v[200:203], v[0:3]
	v_mfma_f32_16x16x32_bf16 v[52:55], v[148:151], v[164:167], v[52:55]
	v_mfma_f32_16x16x32_bf16 v[44:47], v[156:159], v[164:167], v[44:47]
	v_mfma_f32_16x16x32_bf16 v[36:39], v[148:151], v[172:175], v[36:39]
	v_mfma_f32_16x16x32_bf16 v[28:31], v[156:159], v[172:175], v[28:31]
	v_mfma_f32_16x16x32_bf16 v[16:19], v[148:151], v[196:199], v[16:19]
	v_mfma_f32_16x16x32_bf16 v[12:15], v[156:159], v[196:199], v[12:15]
	v_mfma_f32_16x16x32_bf16 v[4:7], v[148:151], v[220:223], v[4:7]
	v_mfma_f32_16x16x32_bf16 v[0:3], v[156:159], v[220:223], v[0:3]
	s_setprio 0
	s_add_i32 s53, s53, 2
	s_add_u32 s51, s51, 0x100
	s_addc_u32 s52, s52, 0
	s_cmpk_gt_u32 s53, 0x7d
	s_mov_b64 s[4:5], s[24:25]
	s_cbranch_scc1 .Lrot_x_1269
	s_add_u32 s24, s4, 0x100
	s_addc_u32 s25, s5, 0
	s_add_i32 s54, 0, 0x10000
	s_cmpk_eq_i32 s53, 0x7c
	s_cselect_b32 s29, s19, s25
	s_cselect_b32 s28, s49, s24
	s_cselect_b32 s27, s17, s52
	s_cselect_b32 s26, s50, s51
	s_add_i32 s55, 0, 0x14000
	s_barrier
	s_branch .Lrot_h_1269
